# G2 gate-line touch prefetch at loop top (4 dword loads of the gate rows) on top of v21
# baseline (speedup 1.0000x reference)
; #define GLOAD(RA, RB, kt_)                                                         \
;   _Pragma("unroll") for (int i = 0; i < 4; ++i) {                                  \
;     RA[i] = *(const u32x4*)(ap + (size_t)(32 * i) * lda + ((kt_) << 6));           \
;     RB[i] = *(const u32x4*)(bp + (size_t)(32 * i) * ldb + ((kt_) << 6));           \
;   }
; #define SWRITE(RA, RB, buf_)                                                       \
;   _Pragma("unroll") for (int i = 0; i < 4; ++i) {                                  \
;     *(u32x4*)(wA + (buf_) * BUF + 32 * i * LDS_STRIDE) = RA[i];                    \
;     *(u32x4*)(wB + (buf_) * BUF + 32 * i * LDS_STRIDE) = RB[i];                    \
;   }
; template <bool DEEP>
; __device__ __forceinline__ void gemm_core(const bf16_t* __restrict__ A, int lda, const bf16_t* __restrict__ Bt, int ldb,
;                                           int K, f32x4 (&acc)[4][4], char* smem) {
;     ...
;     __syncthreads();
;     SWRITE(ra0, rb0, 0);
;     __syncthreads();
;     for (int kt = 0; kt < nk; ++kt) {
;       const int cur = kt & 1;
;       { const int k1 = min(kt + 1, nk - 1); GLOAD(ra0, rb0, k1); }
;       mma_ktile(cA0 + cur * BUF, cB0 + cur * BUF, fo0, fo1, acc);
;       if (kt + 1 < nk) { SWRITE(ra0, rb0, cur ^ 1); }
;       __syncthreads();
;     }
; __device__ __forceinline__ void phase_gemm_merge(const Params& p, char* smem) {
;     ...
;     for (int b = 0; b < 3; ++b) {
;       f32x4 acc[4][4];
; #pragma unroll
;       for (int i = 0; i < 4; ++i)
; #pragma unroll
;         for (int j = 0; j < 4; ++j) acc[i][j] = (f32x4){0.f, 0.f, 0.f, 0.f};
;       gemm_core<false>(BR + (size_t)mt * 128 * 1536 + b * 512, 1536, W + ((size_t)b * 1024 + nt * 128) * 512, 512, 512, acc, smem);
; #pragma unroll
;       for (int i = 0; i < 4; ++i) {
;         const int m = mt * 128 + wm * 64 + i * 16 + (lane & 15);
; #pragma unroll
;         for (int j = 0; j < 4; ++j) {
;           const int n = nt * 128 + wn * 64 + j * 16 + (lane >> 4) * 4;
;           const uint2 gz = *(const uint2*)(POST + (size_t)m * POST_W + QC_GATE + b * 1024 + n);
.LBB0_21:
	s_add_u32 s30, s10, 0xcb20c00
	s_addc_u32 s31, s11, 0
	v_mov_b32_e32 v177, v110
	global_load_dword v187, v177, s[30:31]
	v_add_u32_e32 v177, 0x24000, v177
	global_load_dword v187, v177, s[30:31]
	v_add_u32_e32 v177, 0x24000, v177
	global_load_dword v187, v177, s[30:31]
	v_add_u32_e32 v177, 0x24000, v177
	global_load_dword v187, v177, s[30:31]
	v_mov_b32_e32 v128, v178
	s_mov_b32 s29, 0x237f8000
	v_ashrrev_i32_e32 v126, 3, v128
	v_mad_i64_i32 v[4:5], s[30:31], v126, s78, 0
	v_lshlrev_b32_e32 v6, 4, v128
	v_and_b32_e32 v6, 0x70, v6
	s_add_u32 s30, s13, s16
	v_ashrrev_i32_e32 v127, 31, v126
	v_or_b32_e32 v4, v4, v6
	s_addc_u32 s31, s28, s17
	v_lshl_add_u64 v[36:37], s[30:31], 0, v[4:5]
	v_lshlrev_b64 v[4:5], 10, v[126:127]
	s_add_u32 s30, s10, s14
	v_or_b32_e32 v4, v4, v6
	s_addc_u32 s31, s11, s15
	v_lshl_add_u64 v[32:33], s[30:31], 0, v[4:5]
	v_add_co_u32_e32 v38, vcc, s29, v32
	s_mov_b32 s29, 0x23800000
	s_nop 0
	v_addc_co_u32_e32 v39, vcc, 0, v33, vcc
	v_add_co_u32_e32 v40, vcc, s1, v36
	v_and_b32_e32 v4, 15, v128
	s_nop 0
	v_addc_co_u32_e32 v41, vcc, 0, v37, vcc
	v_add_co_u32_e32 v42, vcc, s29, v32
	v_lshrrev_b32_e32 v7, 1, v128
	s_nop 0
	v_addc_co_u32_e32 v43, vcc, 0, v33, vcc
	v_lshrrev_b32_e32 v5, 4, v128
	v_bfe_u32 v6, v128, 4, 2
	v_bfe_u32 v8, v128, 1, 3
	v_and_or_b32 v4, v7, s79, v4
	v_add_co_u32_e32 v44, vcc, s0, v36
	v_bitop3_b32 v127, v5, v8, 3 bitop3:0x6c
	v_bitop3_b32 v129, v6, v8, 4 bitop3:0x36
	v_lshlrev_b32_e32 v130, 7, v4
	v_xor_b32_e32 v131, v5, v128
	global_load_dwordx4 v[4:7], v[36:37], off
	v_addc_co_u32_e32 v45, vcc, 0, v37, vcc
	s_mov_b32 s29, 0x23808000
	global_load_dwordx4 v[8:11], v[38:39], off
	v_add_co_u32_e32 v46, vcc, s29, v32
	global_load_dwordx4 v[12:15], v[40:41], off
	s_nop 0
	v_addc_co_u32_e32 v47, vcc, 0, v33, vcc
	s_mov_b32 s29, 0x48000
	global_load_dwordx4 v[16:19], v[42:43], off
	v_add_co_u32_e32 v48, vcc, s29, v36
	global_load_dwordx4 v[20:23], v[44:45], off
	s_nop 0
	v_addc_co_u32_e32 v49, vcc, 0, v37, vcc
	s_mov_b32 s29, 0x23810000
	global_load_dwordx4 v[24:27], v[46:47], off
	v_add_co_u32_e32 v50, vcc, s29, v32
	global_load_dwordx4 v[28:31], v[48:49], off
	s_nop 0
	v_addc_co_u32_e32 v51, vcc, 0, v33, vcc
	global_load_dwordx4 v[32:35], v[50:51], off
	v_lshlrev_b32_e32 v131, 4, v131
	v_and_b32_e32 v131, 0x70, v131
	v_lshl_or_b32 v126, v126, 7, v131
	s_barrier
	v_lshlrev_b32_e32 v176, 4, v129
	v_or_b32_e32 v129, v130, v176
	s_add_u32 s16, s16, 0x400
	s_addc_u32 s17, s17, 0
	s_add_u32 s14, s14, 0x100000
	s_addc_u32 s15, s15, 0
	s_cmpk_eq_i32 s16, 0xc00
	s_waitcnt vmcnt(7)
	ds_write_b128 v126, v[4:7]
	s_waitcnt vmcnt(6)
	ds_write_b128 v126, v[8:11] offset:32768
	s_waitcnt vmcnt(5)
	ds_write_b128 v126, v[12:15] offset:4096
	s_waitcnt vmcnt(4)
	ds_write_b128 v126, v[16:19] offset:36864
	s_waitcnt vmcnt(3)
	ds_write_b128 v126, v[20:23] offset:8192
	s_waitcnt vmcnt(2)
	ds_write_b128 v126, v[24:27] offset:40960
	s_waitcnt vmcnt(1)
	ds_write_b128 v126, v[28:31] offset:12288
	s_waitcnt vmcnt(0)
	ds_write_b128 v126, v[32:35] offset:45056
	v_lshlrev_b32_e32 v4, 7, v128
	v_and_b32_e32 v131, 0x2780, v4
	s_waitcnt lgkmcnt(0)
	s_barrier
	global_load_dwordx4 v[4:7], v[36:37], off offset:128
	global_load_dwordx4 v[8:11], v[38:39], off offset:128
	global_load_dwordx4 v[12:15], v[40:41], off offset:128
	global_load_dwordx4 v[16:19], v[42:43], off offset:128
	global_load_dwordx4 v[20:23], v[44:45], off offset:128
	global_load_dwordx4 v[24:27], v[46:47], off offset:128
	global_load_dwordx4 v[28:31], v[48:49], off offset:128
	global_load_dwordx4 v[32:35], v[50:51], off offset:128
	v_lshlrev_b32_e32 v128, 4, v127
	v_or_b32_e32 v127, v130, v128
	v_or_b32_e32 v128, v131, v128
	ds_read_b128 v[132:135], v127
	ds_read_b128 v[136:139], v127 offset:2048
	ds_read_b128 v[140:143], v127 offset:4096
	ds_read_b128 v[144:147], v127 offset:6144
	ds_read_b128 v[148:151], v128 offset:32768
	ds_read_b128 v[152:155], v128 offset:34816
	ds_read_b128 v[156:159], v128 offset:36864
	ds_read_b128 v[160:163], v128 offset:38912
	v_or_b32_e32 v130, v131, v176
	s_waitcnt lgkmcnt(3)
	v_mfma_f32_16x16x32_bf16 v[164:167], v[148:151], v[132:135], 0
	s_waitcnt lgkmcnt(2)
	v_mfma_f32_16x16x32_bf16 v[168:171], v[152:155], v[132:135], 0
	s_waitcnt lgkmcnt(1)
	v_mfma_f32_16x16x32_bf16 v[172:175], v[156:159], v[132:135], 0
	s_waitcnt lgkmcnt(0)
	v_mfma_f32_16x16x32_bf16 v[132:135], v[160:163], v[132:135], 0
	v_mfma_f32_16x16x32_bf16 v[188:191], v[148:151], v[136:139], 0
	v_mfma_f32_16x16x32_bf16 v[192:195], v[152:155], v[136:139], 0
	v_mfma_f32_16x16x32_bf16 v[196:199], v[156:159], v[136:139], 0
	v_mfma_f32_16x16x32_bf16 v[136:139], v[160:163], v[136:139], 0
	v_mfma_f32_16x16x32_bf16 v[200:203], v[148:151], v[140:143], 0
	v_mfma_f32_16x16x32_bf16 v[204:207], v[152:155], v[140:143], 0
	v_mfma_f32_16x16x32_bf16 v[208:211], v[156:159], v[140:143], 0
	v_mfma_f32_16x16x32_bf16 v[140:143], v[160:163], v[140:143], 0
	v_mfma_f32_16x16x32_bf16 v[148:151], v[148:151], v[144:147], 0
	v_mfma_f32_16x16x32_bf16 v[152:155], v[152:155], v[144:147], 0
	v_mfma_f32_16x16x32_bf16 v[156:159], v[156:159], v[144:147], 0
	v_mfma_f32_16x16x32_bf16 v[144:147], v[160:163], v[144:147], 0
	ds_read_b128 v[160:163], v129
	ds_read_b128 v[212:215], v129 offset:2048
	ds_read_b128 v[216:219], v129 offset:4096
	ds_read_b128 v[220:223], v129 offset:6144
	ds_read_b128 v[224:227], v130 offset:32768
	ds_read_b128 v[228:231], v130 offset:34816
	ds_read_b128 v[232:235], v130 offset:36864
	ds_read_b128 v[236:239], v130 offset:38912
	s_waitcnt vmcnt(7)
	ds_write_b128 v126, v[4:7] offset:16384
	s_waitcnt vmcnt(6)
	ds_write_b128 v126, v[8:11] offset:49152
	s_waitcnt vmcnt(5)
	ds_write_b128 v126, v[12:15] offset:20480
	s_waitcnt vmcnt(4)
	ds_write_b128 v126, v[16:19] offset:53248
	s_waitcnt vmcnt(3)
	ds_write_b128 v126, v[20:23] offset:24576
	s_waitcnt vmcnt(2)
	ds_write_b128 v126, v[24:27] offset:57344
	s_waitcnt vmcnt(1)
	ds_write_b128 v126, v[28:31] offset:28672
	s_waitcnt vmcnt(0)
	ds_write_b128 v126, v[32:35] offset:61440
	s_waitcnt lgkmcnt(0)
	s_barrier
; #define GLOAD(RA, RB, kt_)                                                         \
;   _Pragma("unroll") for (int i = 0; i < 4; ++i) {                                  \
;     RA[i] = *(const u32x4*)(ap + (size_t)(32 * i) * lda + ((kt_) << 6));           \
;     RB[i] = *(const u32x4*)(bp + (size_t)(32 * i) * ldb + ((kt_) << 6));           \
;   }
; #define SWRITE(RA, RB, buf_)                                                       \
;   _Pragma("unroll") for (int i = 0; i < 4; ++i) {                                  \
;     *(u32x4*)(wA + (buf_) * BUF + 32 * i * LDS_STRIDE) = RA[i];                    \
;     *(u32x4*)(wB + (buf_) * BUF + 32 * i * LDS_STRIDE) = RB[i];                    \
;   }
; __device__ __forceinline__ void mma_ktile(const bf16_t* cA, const bf16_t* cB, int fo0, int fo1, f32x4 (&acc)[4][4]) {
; #pragma unroll
;   for (int ks = 0; ks < 2; ++ks) {
;     const int fo = ks ? fo1 : fo0;
;     bf16x8 af[4], bfr[4];
; #pragma unroll
;     for (int i = 0; i < 4; ++i) af[i] = *(const bf16x8*)(cA + i * 16 * LDS_STRIDE + fo);
; #pragma unroll
;     for (int j = 0; j < 4; ++j) bfr[j] = *(const bf16x8*)(cB + j * 16 * LDS_STRIDE + fo);
; #pragma unroll
;     for (int i = 0; i < 4; ++i)
; #pragma unroll
;       for (int j = 0; j < 4; ++j)
;         acc[i][j] = __builtin_amdgcn_mfma_f32_16x16x32_bf16(bfr[j], af[i], acc[i][j], 0, 0, 0);
;   }
; }
; template <bool DEEP>
; __device__ __forceinline__ void gemm_core(const bf16_t* __restrict__ A, int lda, const bf16_t* __restrict__ Bt, int ldb,
;                                           int K, f32x4 (&acc)[4][4], char* smem) {
;     ...
;     for (int kt = 0; kt < nk; ++kt) {
;       const int cur = kt & 1;
;       { const int k1 = min(kt + 1, nk - 1); GLOAD(ra0, rb0, k1); }
;       mma_ktile(cA0 + cur * BUF, cB0 + cur * BUF, fo0, fo1, acc);
;       if (kt + 1 < nk) { SWRITE(ra0, rb0, cur ^ 1); }
;       __syncthreads();
;     }
	global_load_dwordx4 v[4:7], v[36:37], off offset:256
	global_load_dwordx4 v[8:11], v[38:39], off offset:256
	global_load_dwordx4 v[12:15], v[40:41], off offset:256
	global_load_dwordx4 v[16:19], v[42:43], off offset:256
	global_load_dwordx4 v[20:23], v[44:45], off offset:256
	global_load_dwordx4 v[24:27], v[46:47], off offset:256
	global_load_dwordx4 v[28:31], v[48:49], off offset:256
	global_load_dwordx4 v[32:35], v[50:51], off offset:256
	v_mfma_f32_16x16x32_bf16 v[164:167], v[224:227], v[160:163], v[164:167]
	v_mfma_f32_16x16x32_bf16 v[168:171], v[228:231], v[160:163], v[168:171]
	v_mfma_f32_16x16x32_bf16 v[172:175], v[232:235], v[160:163], v[172:175]
	v_mfma_f32_16x16x32_bf16 v[132:135], v[236:239], v[160:163], v[132:135]
	v_mfma_f32_16x16x32_bf16 v[160:163], v[224:227], v[212:215], v[188:191]
	v_mfma_f32_16x16x32_bf16 v[188:191], v[228:231], v[212:215], v[192:195]
	v_mfma_f32_16x16x32_bf16 v[192:195], v[232:235], v[212:215], v[196:199]
	v_mfma_f32_16x16x32_bf16 v[136:139], v[236:239], v[212:215], v[136:139]
	v_mfma_f32_16x16x32_bf16 v[196:199], v[224:227], v[216:219], v[200:203]
	v_mfma_f32_16x16x32_bf16 v[200:203], v[228:231], v[216:219], v[204:207]
	v_mfma_f32_16x16x32_bf16 v[204:207], v[232:235], v[216:219], v[208:211]
	v_mfma_f32_16x16x32_bf16 v[140:143], v[236:239], v[216:219], v[140:143]
	v_mfma_f32_16x16x32_bf16 v[148:151], v[224:227], v[220:223], v[148:151]
	v_mfma_f32_16x16x32_bf16 v[152:155], v[228:231], v[220:223], v[152:155]
	v_mfma_f32_16x16x32_bf16 v[156:159], v[232:235], v[220:223], v[156:159]
	v_mfma_f32_16x16x32_bf16 v[144:147], v[236:239], v[220:223], v[144:147]
	ds_read_b128 v[208:211], v127 offset:16384
	ds_read_b128 v[212:215], v127 offset:18432
	ds_read_b128 v[216:219], v127 offset:20480
	ds_read_b128 v[220:223], v127 offset:22528
	ds_read_b128 v[224:227], v128 offset:49152
	ds_read_b128 v[228:231], v128 offset:51200
	ds_read_b128 v[232:235], v128 offset:53248
	ds_read_b128 v[236:239], v128 offset:55296
	s_waitcnt lgkmcnt(3)
	v_mfma_f32_16x16x32_bf16 v[164:167], v[224:227], v[208:211], v[164:167]
	s_waitcnt lgkmcnt(2)
	v_mfma_f32_16x16x32_bf16 v[168:171], v[228:231], v[208:211], v[168:171]
	s_waitcnt lgkmcnt(1)
	v_mfma_f32_16x16x32_bf16 v[172:175], v[232:235], v[208:211], v[172:175]
	s_waitcnt lgkmcnt(0)
	v_mfma_f32_16x16x32_bf16 v[132:135], v[236:239], v[208:211], v[132:135]
	v_mfma_f32_16x16x32_bf16 v[160:163], v[224:227], v[212:215], v[160:163]
	v_mfma_f32_16x16x32_bf16 v[188:191], v[228:231], v[212:215], v[188:191]
	v_mfma_f32_16x16x32_bf16 v[192:195], v[232:235], v[212:215], v[192:195]
	v_mfma_f32_16x16x32_bf16 v[136:139], v[236:239], v[212:215], v[136:139]
	v_mfma_f32_16x16x32_bf16 v[196:199], v[224:227], v[216:219], v[196:199]
	v_mfma_f32_16x16x32_bf16 v[200:203], v[228:231], v[216:219], v[200:203]
	v_mfma_f32_16x16x32_bf16 v[204:207], v[232:235], v[216:219], v[204:207]
	v_mfma_f32_16x16x32_bf16 v[140:143], v[236:239], v[216:219], v[140:143]
	v_mfma_f32_16x16x32_bf16 v[148:151], v[224:227], v[220:223], v[148:151]
	v_mfma_f32_16x16x32_bf16 v[152:155], v[228:231], v[220:223], v[152:155]
	v_mfma_f32_16x16x32_bf16 v[156:159], v[232:235], v[220:223], v[156:159]
	v_mfma_f32_16x16x32_bf16 v[144:147], v[236:239], v[220:223], v[144:147]
	ds_read_b128 v[208:211], v129 offset:16384
	ds_read_b128 v[212:215], v129 offset:18432
	ds_read_b128 v[216:219], v129 offset:20480
	ds_read_b128 v[220:223], v129 offset:22528
	ds_read_b128 v[224:227], v130 offset:49152
	ds_read_b128 v[228:231], v130 offset:51200
	ds_read_b128 v[232:235], v130 offset:53248
	ds_read_b128 v[236:239], v130 offset:55296
	s_waitcnt vmcnt(7)
	ds_write_b128 v126, v[4:7]
	s_waitcnt vmcnt(6)
	ds_write_b128 v126, v[8:11] offset:32768
	s_waitcnt vmcnt(5)
	ds_write_b128 v126, v[12:15] offset:4096
	s_waitcnt vmcnt(4)
	ds_write_b128 v126, v[16:19] offset:36864
	s_waitcnt vmcnt(3)
	ds_write_b128 v126, v[20:23] offset:8192
	s_waitcnt vmcnt(2)
	ds_write_b128 v126, v[24:27] offset:40960
	s_waitcnt vmcnt(1)
	ds_write_b128 v126, v[28:31] offset:12288
	s_waitcnt vmcnt(0)
	ds_write_b128 v126, v[32:35] offset:45056
	s_waitcnt lgkmcnt(0)
	s_barrier
	global_load_dwordx4 v[4:7], v[36:37], off offset:384
	global_load_dwordx4 v[8:11], v[38:39], off offset:384
	global_load_dwordx4 v[12:15], v[40:41], off offset:384
	global_load_dwordx4 v[16:19], v[42:43], off offset:384
	global_load_dwordx4 v[20:23], v[44:45], off offset:384
	global_load_dwordx4 v[24:27], v[46:47], off offset:384
	global_load_dwordx4 v[28:31], v[48:49], off offset:384
	global_load_dwordx4 v[32:35], v[50:51], off offset:384
	v_mfma_f32_16x16x32_bf16 v[164:167], v[224:227], v[208:211], v[164:167]
	v_mfma_f32_16x16x32_bf16 v[168:171], v[228:231], v[208:211], v[168:171]
	v_mfma_f32_16x16x32_bf16 v[172:175], v[232:235], v[208:211], v[172:175]
	v_mfma_f32_16x16x32_bf16 v[132:135], v[236:239], v[208:211], v[132:135]
	v_mfma_f32_16x16x32_bf16 v[160:163], v[224:227], v[212:215], v[160:163]
	v_mfma_f32_16x16x32_bf16 v[188:191], v[228:231], v[212:215], v[188:191]
	v_mfma_f32_16x16x32_bf16 v[192:195], v[232:235], v[212:215], v[192:195]
	v_mfma_f32_16x16x32_bf16 v[136:139], v[236:239], v[212:215], v[136:139]
	v_mfma_f32_16x16x32_bf16 v[196:199], v[224:227], v[216:219], v[196:199]
	v_mfma_f32_16x16x32_bf16 v[200:203], v[228:231], v[216:219], v[200:203]
	v_mfma_f32_16x16x32_bf16 v[204:207], v[232:235], v[216:219], v[204:207]
	v_mfma_f32_16x16x32_bf16 v[140:143], v[236:239], v[216:219], v[140:143]
	v_mfma_f32_16x16x32_bf16 v[148:151], v[224:227], v[220:223], v[148:151]
	v_mfma_f32_16x16x32_bf16 v[152:155], v[228:231], v[220:223], v[152:155]
	v_mfma_f32_16x16x32_bf16 v[156:159], v[232:235], v[220:223], v[156:159]
	v_mfma_f32_16x16x32_bf16 v[144:147], v[236:239], v[220:223], v[144:147]
	ds_read_b128 v[208:211], v127
	ds_read_b128 v[212:215], v127 offset:2048
	ds_read_b128 v[216:219], v127 offset:4096
	ds_read_b128 v[220:223], v127 offset:6144
	ds_read_b128 v[224:227], v128 offset:32768
	ds_read_b128 v[228:231], v128 offset:34816
	ds_read_b128 v[232:235], v128 offset:36864
	ds_read_b128 v[236:239], v128 offset:38912
	s_waitcnt lgkmcnt(3)
; #define GLOAD(RA, RB, kt_)                                                         \
;   _Pragma("unroll") for (int i = 0; i < 4; ++i) {                                  \
;     RA[i] = *(const u32x4*)(ap + (size_t)(32 * i) * lda + ((kt_) << 6));           \
;     RB[i] = *(const u32x4*)(bp + (size_t)(32 * i) * ldb + ((kt_) << 6));           \
;   }
; #define SWRITE(RA, RB, buf_)                                                       \
;   _Pragma("unroll") for (int i = 0; i < 4; ++i) {                                  \
;     *(u32x4*)(wA + (buf_) * BUF + 32 * i * LDS_STRIDE) = RA[i];                    \
;     *(u32x4*)(wB + (buf_) * BUF + 32 * i * LDS_STRIDE) = RB[i];                    \
;   }
; __device__ __forceinline__ void mma_ktile(const bf16_t* cA, const bf16_t* cB, int fo0, int fo1, f32x4 (&acc)[4][4]) {
; #pragma unroll
;   for (int ks = 0; ks < 2; ++ks) {
;     const int fo = ks ? fo1 : fo0;
;     bf16x8 af[4], bfr[4];
; #pragma unroll
;     for (int i = 0; i < 4; ++i) af[i] = *(const bf16x8*)(cA + i * 16 * LDS_STRIDE + fo);
; #pragma unroll
;     for (int j = 0; j < 4; ++j) bfr[j] = *(const bf16x8*)(cB + j * 16 * LDS_STRIDE + fo);
; #pragma unroll
;     for (int i = 0; i < 4; ++i)
; #pragma unroll
;       for (int j = 0; j < 4; ++j)
;         acc[i][j] = __builtin_amdgcn_mfma_f32_16x16x32_bf16(bfr[j], af[i], acc[i][j], 0, 0, 0);
;   }
; }
; template <bool DEEP>
; __device__ __forceinline__ void gemm_core(const bf16_t* __restrict__ A, int lda, const bf16_t* __restrict__ Bt, int ldb,
;                                           int K, f32x4 (&acc)[4][4], char* smem) {
;     ...
;     for (int kt = 0; kt < nk; ++kt) {
;       const int cur = kt & 1;
;       { const int k1 = min(kt + 1, nk - 1); GLOAD(ra0, rb0, k1); }
;       mma_ktile(cA0 + cur * BUF, cB0 + cur * BUF, fo0, fo1, acc);
;       if (kt + 1 < nk) { SWRITE(ra0, rb0, cur ^ 1); }
;       __syncthreads();
;     }
	v_mfma_f32_16x16x32_bf16 v[164:167], v[224:227], v[208:211], v[164:167]
	s_waitcnt lgkmcnt(2)
	v_mfma_f32_16x16x32_bf16 v[168:171], v[228:231], v[208:211], v[168:171]
	s_waitcnt lgkmcnt(1)
	v_mfma_f32_16x16x32_bf16 v[172:175], v[232:235], v[208:211], v[172:175]
	s_waitcnt lgkmcnt(0)
	v_mfma_f32_16x16x32_bf16 v[132:135], v[236:239], v[208:211], v[132:135]
	v_mfma_f32_16x16x32_bf16 v[160:163], v[224:227], v[212:215], v[160:163]
	v_mfma_f32_16x16x32_bf16 v[188:191], v[228:231], v[212:215], v[188:191]
	v_mfma_f32_16x16x32_bf16 v[192:195], v[232:235], v[212:215], v[192:195]
	v_mfma_f32_16x16x32_bf16 v[136:139], v[236:239], v[212:215], v[136:139]
	v_mfma_f32_16x16x32_bf16 v[196:199], v[224:227], v[216:219], v[196:199]
	v_mfma_f32_16x16x32_bf16 v[200:203], v[228:231], v[216:219], v[200:203]
	v_mfma_f32_16x16x32_bf16 v[204:207], v[232:235], v[216:219], v[204:207]
	v_mfma_f32_16x16x32_bf16 v[140:143], v[236:239], v[216:219], v[140:143]
	v_mfma_f32_16x16x32_bf16 v[148:151], v[224:227], v[220:223], v[148:151]
	v_mfma_f32_16x16x32_bf16 v[152:155], v[228:231], v[220:223], v[152:155]
	v_mfma_f32_16x16x32_bf16 v[156:159], v[232:235], v[220:223], v[156:159]
	v_mfma_f32_16x16x32_bf16 v[144:147], v[236:239], v[220:223], v[144:147]
	ds_read_b128 v[208:211], v129
	ds_read_b128 v[212:215], v129 offset:2048
	ds_read_b128 v[216:219], v129 offset:4096
	ds_read_b128 v[220:223], v129 offset:6144
	ds_read_b128 v[224:227], v130 offset:32768
	ds_read_b128 v[228:231], v130 offset:34816
	ds_read_b128 v[232:235], v130 offset:36864
	ds_read_b128 v[236:239], v130 offset:38912
	s_waitcnt vmcnt(7)
	ds_write_b128 v126, v[4:7] offset:16384
	s_waitcnt vmcnt(6)
	ds_write_b128 v126, v[8:11] offset:49152
	s_waitcnt vmcnt(5)
	ds_write_b128 v126, v[12:15] offset:20480
	s_waitcnt vmcnt(4)
	ds_write_b128 v126, v[16:19] offset:53248
	s_waitcnt vmcnt(3)
	ds_write_b128 v126, v[20:23] offset:24576
	s_waitcnt vmcnt(2)
	ds_write_b128 v126, v[24:27] offset:57344
	s_waitcnt vmcnt(1)
	ds_write_b128 v126, v[28:31] offset:28672
	s_waitcnt vmcnt(0)
	ds_write_b128 v126, v[32:35] offset:61440
	s_waitcnt lgkmcnt(0)
	s_barrier
	global_load_dwordx4 v[4:7], v[36:37], off offset:512
	global_load_dwordx4 v[8:11], v[38:39], off offset:512
	global_load_dwordx4 v[12:15], v[40:41], off offset:512
	global_load_dwordx4 v[16:19], v[42:43], off offset:512
	global_load_dwordx4 v[20:23], v[44:45], off offset:512
	global_load_dwordx4 v[24:27], v[46:47], off offset:512
	global_load_dwordx4 v[28:31], v[48:49], off offset:512
	global_load_dwordx4 v[32:35], v[50:51], off offset:512
	v_mfma_f32_16x16x32_bf16 v[164:167], v[224:227], v[208:211], v[164:167]
	v_mfma_f32_16x16x32_bf16 v[168:171], v[228:231], v[208:211], v[168:171]
	v_mfma_f32_16x16x32_bf16 v[172:175], v[232:235], v[208:211], v[172:175]
	v_mfma_f32_16x16x32_bf16 v[132:135], v[236:239], v[208:211], v[132:135]
	v_mfma_f32_16x16x32_bf16 v[160:163], v[224:227], v[212:215], v[160:163]
	v_mfma_f32_16x16x32_bf16 v[188:191], v[228:231], v[212:215], v[188:191]
	v_mfma_f32_16x16x32_bf16 v[192:195], v[232:235], v[212:215], v[192:195]
	v_mfma_f32_16x16x32_bf16 v[136:139], v[236:239], v[212:215], v[136:139]
	v_mfma_f32_16x16x32_bf16 v[196:199], v[224:227], v[216:219], v[196:199]
	v_mfma_f32_16x16x32_bf16 v[200:203], v[228:231], v[216:219], v[200:203]
	v_mfma_f32_16x16x32_bf16 v[204:207], v[232:235], v[216:219], v[204:207]
	v_mfma_f32_16x16x32_bf16 v[140:143], v[236:239], v[216:219], v[140:143]
	v_mfma_f32_16x16x32_bf16 v[148:151], v[224:227], v[220:223], v[148:151]
	v_mfma_f32_16x16x32_bf16 v[152:155], v[228:231], v[220:223], v[152:155]
	v_mfma_f32_16x16x32_bf16 v[156:159], v[232:235], v[220:223], v[156:159]
	v_mfma_f32_16x16x32_bf16 v[144:147], v[236:239], v[220:223], v[144:147]
	ds_read_b128 v[208:211], v127 offset:16384
	ds_read_b128 v[212:215], v127 offset:18432
	ds_read_b128 v[216:219], v127 offset:20480
	ds_read_b128 v[220:223], v127 offset:22528
	ds_read_b128 v[224:227], v128 offset:49152
	ds_read_b128 v[228:231], v128 offset:51200
	ds_read_b128 v[232:235], v128 offset:53248
	ds_read_b128 v[236:239], v128 offset:55296
	s_waitcnt lgkmcnt(3)
	v_mfma_f32_16x16x32_bf16 v[164:167], v[224:227], v[208:211], v[164:167]
	s_waitcnt lgkmcnt(2)
	v_mfma_f32_16x16x32_bf16 v[168:171], v[228:231], v[208:211], v[168:171]
	s_waitcnt lgkmcnt(1)
	v_mfma_f32_16x16x32_bf16 v[172:175], v[232:235], v[208:211], v[172:175]
	s_waitcnt lgkmcnt(0)
	v_mfma_f32_16x16x32_bf16 v[132:135], v[236:239], v[208:211], v[132:135]
	v_mfma_f32_16x16x32_bf16 v[160:163], v[224:227], v[212:215], v[160:163]
	v_mfma_f32_16x16x32_bf16 v[188:191], v[228:231], v[212:215], v[188:191]
	v_mfma_f32_16x16x32_bf16 v[192:195], v[232:235], v[212:215], v[192:195]
	v_mfma_f32_16x16x32_bf16 v[136:139], v[236:239], v[212:215], v[136:139]
	v_mfma_f32_16x16x32_bf16 v[196:199], v[224:227], v[216:219], v[196:199]
	v_mfma_f32_16x16x32_bf16 v[200:203], v[228:231], v[216:219], v[200:203]
	v_mfma_f32_16x16x32_bf16 v[204:207], v[232:235], v[216:219], v[204:207]
	v_mfma_f32_16x16x32_bf16 v[140:143], v[236:239], v[216:219], v[140:143]
	v_mfma_f32_16x16x32_bf16 v[148:151], v[224:227], v[220:223], v[148:151]
	v_mfma_f32_16x16x32_bf16 v[152:155], v[228:231], v[220:223], v[152:155]
	v_mfma_f32_16x16x32_bf16 v[156:159], v[232:235], v[220:223], v[156:159]
	v_mfma_f32_16x16x32_bf16 v[144:147], v[236:239], v[220:223], v[144:147]
	ds_read_b128 v[208:211], v129 offset:16384
	ds_read_b128 v[212:215], v129 offset:18432
	ds_read_b128 v[216:219], v129 offset:20480
	ds_read_b128 v[220:223], v129 offset:22528
	ds_read_b128 v[224:227], v130 offset:49152
	ds_read_b128 v[228:231], v130 offset:51200
	ds_read_b128 v[232:235], v130 offset:53248
	ds_read_b128 v[236:239], v130 offset:55296
	s_waitcnt vmcnt(7)
	ds_write_b128 v126, v[4:7]
	s_waitcnt vmcnt(6)
	ds_write_b128 v126, v[8:11] offset:32768
	s_waitcnt vmcnt(5)
	ds_write_b128 v126, v[12:15] offset:4096
	s_waitcnt vmcnt(4)
	ds_write_b128 v126, v[16:19] offset:36864
	s_waitcnt vmcnt(3)
	ds_write_b128 v126, v[20:23] offset:8192
	s_waitcnt vmcnt(2)
	ds_write_b128 v126, v[24:27] offset:40960
	s_waitcnt vmcnt(1)
	ds_write_b128 v126, v[28:31] offset:12288
	s_waitcnt vmcnt(0)
	ds_write_b128 v126, v[32:35] offset:45056
	s_waitcnt lgkmcnt(0)
	s_barrier
; #define GLOAD(RA, RB, kt_)                                                         \
;   _Pragma("unroll") for (int i = 0; i < 4; ++i) {                                  \
;     RA[i] = *(const u32x4*)(ap + (size_t)(32 * i) * lda + ((kt_) << 6));           \
;     RB[i] = *(const u32x4*)(bp + (size_t)(32 * i) * ldb + ((kt_) << 6));           \
;   }
; #define SWRITE(RA, RB, buf_)                                                       \
;   _Pragma("unroll") for (int i = 0; i < 4; ++i) {                                  \
;     *(u32x4*)(wA + (buf_) * BUF + 32 * i * LDS_STRIDE) = RA[i];                    \
;     *(u32x4*)(wB + (buf_) * BUF + 32 * i * LDS_STRIDE) = RB[i];                    \
;   }
; __device__ __forceinline__ void mma_ktile(const bf16_t* cA, const bf16_t* cB, int fo0, int fo1, f32x4 (&acc)[4][4]) {
; #pragma unroll
;   for (int ks = 0; ks < 2; ++ks) {
;     const int fo = ks ? fo1 : fo0;
;     bf16x8 af[4], bfr[4];
; #pragma unroll
;     for (int i = 0; i < 4; ++i) af[i] = *(const bf16x8*)(cA + i * 16 * LDS_STRIDE + fo);
; #pragma unroll
;     for (int j = 0; j < 4; ++j) bfr[j] = *(const bf16x8*)(cB + j * 16 * LDS_STRIDE + fo);
; #pragma unroll
;     for (int i = 0; i < 4; ++i)
; #pragma unroll
;       for (int j = 0; j < 4; ++j)
;         acc[i][j] = __builtin_amdgcn_mfma_f32_16x16x32_bf16(bfr[j], af[i], acc[i][j], 0, 0, 0);
;   }
; }
; template <bool DEEP>
; __device__ __forceinline__ void gemm_core(const bf16_t* __restrict__ A, int lda, const bf16_t* __restrict__ Bt, int ldb,
;                                           int K, f32x4 (&acc)[4][4], char* smem) {
;     ...
;     for (int kt = 0; kt < nk; ++kt) {
;       const int cur = kt & 1;
;       { const int k1 = min(kt + 1, nk - 1); GLOAD(ra0, rb0, k1); }
;       mma_ktile(cA0 + cur * BUF, cB0 + cur * BUF, fo0, fo1, acc);
;       if (kt + 1 < nk) { SWRITE(ra0, rb0, cur ^ 1); }
;       __syncthreads();
;     }
	global_load_dwordx4 v[4:7], v[36:37], off offset:640
	global_load_dwordx4 v[8:11], v[38:39], off offset:640
	global_load_dwordx4 v[12:15], v[40:41], off offset:640
	global_load_dwordx4 v[16:19], v[42:43], off offset:640
	global_load_dwordx4 v[20:23], v[44:45], off offset:640
	global_load_dwordx4 v[24:27], v[46:47], off offset:640
	global_load_dwordx4 v[28:31], v[48:49], off offset:640
	global_load_dwordx4 v[32:35], v[50:51], off offset:640
	v_mfma_f32_16x16x32_bf16 v[164:167], v[224:227], v[208:211], v[164:167]
	v_mfma_f32_16x16x32_bf16 v[168:171], v[228:231], v[208:211], v[168:171]
	v_mfma_f32_16x16x32_bf16 v[172:175], v[232:235], v[208:211], v[172:175]
	v_mfma_f32_16x16x32_bf16 v[132:135], v[236:239], v[208:211], v[132:135]
	v_mfma_f32_16x16x32_bf16 v[160:163], v[224:227], v[212:215], v[160:163]
	v_mfma_f32_16x16x32_bf16 v[188:191], v[228:231], v[212:215], v[188:191]
	v_mfma_f32_16x16x32_bf16 v[192:195], v[232:235], v[212:215], v[192:195]
	v_mfma_f32_16x16x32_bf16 v[136:139], v[236:239], v[212:215], v[136:139]
	v_mfma_f32_16x16x32_bf16 v[196:199], v[224:227], v[216:219], v[196:199]
	v_mfma_f32_16x16x32_bf16 v[200:203], v[228:231], v[216:219], v[200:203]
	v_mfma_f32_16x16x32_bf16 v[204:207], v[232:235], v[216:219], v[204:207]
	v_mfma_f32_16x16x32_bf16 v[140:143], v[236:239], v[216:219], v[140:143]
	v_mfma_f32_16x16x32_bf16 v[148:151], v[224:227], v[220:223], v[148:151]
	v_mfma_f32_16x16x32_bf16 v[152:155], v[228:231], v[220:223], v[152:155]
	v_mfma_f32_16x16x32_bf16 v[156:159], v[232:235], v[220:223], v[156:159]
	v_mfma_f32_16x16x32_bf16 v[144:147], v[236:239], v[220:223], v[144:147]
	ds_read_b128 v[208:211], v127
	ds_read_b128 v[212:215], v127 offset:2048
	ds_read_b128 v[216:219], v127 offset:4096
	ds_read_b128 v[220:223], v127 offset:6144
	ds_read_b128 v[224:227], v128 offset:32768
	ds_read_b128 v[228:231], v128 offset:34816
	ds_read_b128 v[232:235], v128 offset:36864
	ds_read_b128 v[236:239], v128 offset:38912
	s_waitcnt lgkmcnt(3)
	v_mfma_f32_16x16x32_bf16 v[164:167], v[224:227], v[208:211], v[164:167]
	s_waitcnt lgkmcnt(2)
	v_mfma_f32_16x16x32_bf16 v[168:171], v[228:231], v[208:211], v[168:171]
	s_waitcnt lgkmcnt(1)
	v_mfma_f32_16x16x32_bf16 v[172:175], v[232:235], v[208:211], v[172:175]
	s_waitcnt lgkmcnt(0)
	v_mfma_f32_16x16x32_bf16 v[132:135], v[236:239], v[208:211], v[132:135]
	v_mfma_f32_16x16x32_bf16 v[160:163], v[224:227], v[212:215], v[160:163]
	v_mfma_f32_16x16x32_bf16 v[188:191], v[228:231], v[212:215], v[188:191]
	v_mfma_f32_16x16x32_bf16 v[192:195], v[232:235], v[212:215], v[192:195]
	v_mfma_f32_16x16x32_bf16 v[136:139], v[236:239], v[212:215], v[136:139]
	v_mfma_f32_16x16x32_bf16 v[196:199], v[224:227], v[216:219], v[196:199]
	v_mfma_f32_16x16x32_bf16 v[200:203], v[228:231], v[216:219], v[200:203]
	v_mfma_f32_16x16x32_bf16 v[204:207], v[232:235], v[216:219], v[204:207]
	v_mfma_f32_16x16x32_bf16 v[140:143], v[236:239], v[216:219], v[140:143]
	v_mfma_f32_16x16x32_bf16 v[148:151], v[224:227], v[220:223], v[148:151]
	v_mfma_f32_16x16x32_bf16 v[152:155], v[228:231], v[220:223], v[152:155]
	v_mfma_f32_16x16x32_bf16 v[156:159], v[232:235], v[220:223], v[156:159]
	v_mfma_f32_16x16x32_bf16 v[144:147], v[236:239], v[220:223], v[144:147]
	ds_read_b128 v[208:211], v129
	ds_read_b128 v[212:215], v129 offset:2048
	ds_read_b128 v[216:219], v129 offset:4096
	ds_read_b128 v[220:223], v129 offset:6144
	ds_read_b128 v[224:227], v130 offset:32768
	ds_read_b128 v[228:231], v130 offset:34816
	ds_read_b128 v[232:235], v130 offset:36864
	ds_read_b128 v[236:239], v130 offset:38912
	s_waitcnt vmcnt(7)
	ds_write_b128 v126, v[4:7] offset:16384
	s_waitcnt vmcnt(6)
	ds_write_b128 v126, v[8:11] offset:49152
	s_waitcnt vmcnt(5)
	ds_write_b128 v126, v[12:15] offset:20480
	s_waitcnt vmcnt(4)
	ds_write_b128 v126, v[16:19] offset:53248
	s_waitcnt vmcnt(3)
	ds_write_b128 v126, v[20:23] offset:24576
	s_waitcnt vmcnt(2)
	ds_write_b128 v126, v[24:27] offset:57344
	s_waitcnt vmcnt(1)
	ds_write_b128 v126, v[28:31] offset:28672
	s_waitcnt vmcnt(0)
	ds_write_b128 v126, v[32:35] offset:61440
	s_waitcnt lgkmcnt(0)
	s_barrier
	global_load_dwordx4 v[4:7], v[36:37], off offset:768
	global_load_dwordx4 v[8:11], v[38:39], off offset:768
	global_load_dwordx4 v[12:15], v[40:41], off offset:768
	global_load_dwordx4 v[16:19], v[42:43], off offset:768
	global_load_dwordx4 v[20:23], v[44:45], off offset:768
	global_load_dwordx4 v[24:27], v[46:47], off offset:768
	global_load_dwordx4 v[28:31], v[48:49], off offset:768
	global_load_dwordx4 v[32:35], v[50:51], off offset:768
	v_mfma_f32_16x16x32_bf16 v[164:167], v[224:227], v[208:211], v[164:167]
	v_mfma_f32_16x16x32_bf16 v[168:171], v[228:231], v[208:211], v[168:171]
	v_mfma_f32_16x16x32_bf16 v[172:175], v[232:235], v[208:211], v[172:175]
	v_mfma_f32_16x16x32_bf16 v[132:135], v[236:239], v[208:211], v[132:135]
	v_mfma_f32_16x16x32_bf16 v[160:163], v[224:227], v[212:215], v[160:163]
	v_mfma_f32_16x16x32_bf16 v[188:191], v[228:231], v[212:215], v[188:191]
	v_mfma_f32_16x16x32_bf16 v[192:195], v[232:235], v[212:215], v[192:195]
	v_mfma_f32_16x16x32_bf16 v[136:139], v[236:239], v[212:215], v[136:139]
	v_mfma_f32_16x16x32_bf16 v[196:199], v[224:227], v[216:219], v[196:199]
	v_mfma_f32_16x16x32_bf16 v[200:203], v[228:231], v[216:219], v[200:203]
	v_mfma_f32_16x16x32_bf16 v[204:207], v[232:235], v[216:219], v[204:207]
	v_mfma_f32_16x16x32_bf16 v[140:143], v[236:239], v[216:219], v[140:143]
	v_mfma_f32_16x16x32_bf16 v[148:151], v[224:227], v[220:223], v[148:151]
	v_mfma_f32_16x16x32_bf16 v[152:155], v[228:231], v[220:223], v[152:155]
	v_mfma_f32_16x16x32_bf16 v[156:159], v[232:235], v[220:223], v[156:159]
	v_mfma_f32_16x16x32_bf16 v[144:147], v[236:239], v[220:223], v[144:147]
	ds_read_b128 v[208:211], v127 offset:16384
	ds_read_b128 v[212:215], v127 offset:18432
	ds_read_b128 v[216:219], v127 offset:20480
	ds_read_b128 v[220:223], v127 offset:22528
	ds_read_b128 v[224:227], v128 offset:49152
	ds_read_b128 v[228:231], v128 offset:51200
	ds_read_b128 v[232:235], v128 offset:53248
	ds_read_b128 v[236:239], v128 offset:55296
	s_waitcnt lgkmcnt(3)
; #define GLOAD(RA, RB, kt_)                                                         \
;   _Pragma("unroll") for (int i = 0; i < 4; ++i) {                                  \
;     RA[i] = *(const u32x4*)(ap + (size_t)(32 * i) * lda + ((kt_) << 6));           \
;     RB[i] = *(const u32x4*)(bp + (size_t)(32 * i) * ldb + ((kt_) << 6));           \
;   }
; #define SWRITE(RA, RB, buf_)                                                       \
;   _Pragma("unroll") for (int i = 0; i < 4; ++i) {                                  \
;     *(u32x4*)(wA + (buf_) * BUF + 32 * i * LDS_STRIDE) = RA[i];                    \
;     *(u32x4*)(wB + (buf_) * BUF + 32 * i * LDS_STRIDE) = RB[i];                    \
;   }
; __device__ __forceinline__ void mma_ktile(const bf16_t* cA, const bf16_t* cB, int fo0, int fo1, f32x4 (&acc)[4][4]) {
; #pragma unroll
;   for (int ks = 0; ks < 2; ++ks) {
;     const int fo = ks ? fo1 : fo0;
;     bf16x8 af[4], bfr[4];
; #pragma unroll
;     for (int i = 0; i < 4; ++i) af[i] = *(const bf16x8*)(cA + i * 16 * LDS_STRIDE + fo);
; #pragma unroll
;     for (int j = 0; j < 4; ++j) bfr[j] = *(const bf16x8*)(cB + j * 16 * LDS_STRIDE + fo);
; #pragma unroll
;     for (int i = 0; i < 4; ++i)
; #pragma unroll
;       for (int j = 0; j < 4; ++j)
;         acc[i][j] = __builtin_amdgcn_mfma_f32_16x16x32_bf16(bfr[j], af[i], acc[i][j], 0, 0, 0);
;   }
; }
; template <bool DEEP>
; __device__ __forceinline__ void gemm_core(const bf16_t* __restrict__ A, int lda, const bf16_t* __restrict__ Bt, int ldb,
;                                           int K, f32x4 (&acc)[4][4], char* smem) {
;     ...
;     for (int kt = 0; kt < nk; ++kt) {
;       const int cur = kt & 1;
;       { const int k1 = min(kt + 1, nk - 1); GLOAD(ra0, rb0, k1); }
;       mma_ktile(cA0 + cur * BUF, cB0 + cur * BUF, fo0, fo1, acc);
;       if (kt + 1 < nk) { SWRITE(ra0, rb0, cur ^ 1); }
;       __syncthreads();
;     }
	v_mfma_f32_16x16x32_bf16 v[164:167], v[224:227], v[208:211], v[164:167]
	s_waitcnt lgkmcnt(2)
	v_mfma_f32_16x16x32_bf16 v[168:171], v[228:231], v[208:211], v[168:171]
	s_waitcnt lgkmcnt(1)
	v_mfma_f32_16x16x32_bf16 v[172:175], v[232:235], v[208:211], v[172:175]
	s_waitcnt lgkmcnt(0)
	v_mfma_f32_16x16x32_bf16 v[132:135], v[236:239], v[208:211], v[132:135]
	v_mfma_f32_16x16x32_bf16 v[160:163], v[224:227], v[212:215], v[160:163]
	v_mfma_f32_16x16x32_bf16 v[188:191], v[228:231], v[212:215], v[188:191]
	v_mfma_f32_16x16x32_bf16 v[192:195], v[232:235], v[212:215], v[192:195]
	v_mfma_f32_16x16x32_bf16 v[136:139], v[236:239], v[212:215], v[136:139]
	v_mfma_f32_16x16x32_bf16 v[196:199], v[224:227], v[216:219], v[196:199]
	v_mfma_f32_16x16x32_bf16 v[200:203], v[228:231], v[216:219], v[200:203]
	v_mfma_f32_16x16x32_bf16 v[204:207], v[232:235], v[216:219], v[204:207]
	v_mfma_f32_16x16x32_bf16 v[140:143], v[236:239], v[216:219], v[140:143]
	v_mfma_f32_16x16x32_bf16 v[148:151], v[224:227], v[220:223], v[148:151]
	v_mfma_f32_16x16x32_bf16 v[152:155], v[228:231], v[220:223], v[152:155]
	v_mfma_f32_16x16x32_bf16 v[156:159], v[232:235], v[220:223], v[156:159]
	v_mfma_f32_16x16x32_bf16 v[144:147], v[236:239], v[220:223], v[144:147]
	ds_read_b128 v[208:211], v129 offset:16384
	ds_read_b128 v[212:215], v129 offset:18432
	ds_read_b128 v[216:219], v129 offset:20480
	ds_read_b128 v[220:223], v129 offset:22528
	ds_read_b128 v[224:227], v130 offset:49152
	ds_read_b128 v[228:231], v130 offset:51200
	ds_read_b128 v[232:235], v130 offset:53248
	ds_read_b128 v[236:239], v130 offset:55296
	s_waitcnt vmcnt(7)
	ds_write_b128 v126, v[4:7]
	s_waitcnt vmcnt(6)
	ds_write_b128 v126, v[8:11] offset:32768
	s_waitcnt vmcnt(5)
	ds_write_b128 v126, v[12:15] offset:4096
	s_waitcnt vmcnt(4)
	ds_write_b128 v126, v[16:19] offset:36864
	s_waitcnt vmcnt(3)
	ds_write_b128 v126, v[20:23] offset:8192
	s_waitcnt vmcnt(2)
	ds_write_b128 v126, v[24:27] offset:40960
	s_waitcnt vmcnt(1)
	ds_write_b128 v126, v[28:31] offset:12288
	s_waitcnt vmcnt(0)
	ds_write_b128 v126, v[32:35] offset:45056
	s_waitcnt lgkmcnt(0)
	s_barrier
	global_load_dwordx4 v[4:7], v[36:37], off offset:896
	global_load_dwordx4 v[8:11], v[38:39], off offset:896
	global_load_dwordx4 v[12:15], v[40:41], off offset:896
	global_load_dwordx4 v[16:19], v[42:43], off offset:896
	global_load_dwordx4 v[20:23], v[44:45], off offset:896
	global_load_dwordx4 v[24:27], v[46:47], off offset:896
	global_load_dwordx4 v[28:31], v[48:49], off offset:896
	global_load_dwordx4 v[32:35], v[50:51], off offset:896
	v_mfma_f32_16x16x32_bf16 v[164:167], v[224:227], v[208:211], v[164:167]
	v_mfma_f32_16x16x32_bf16 v[168:171], v[228:231], v[208:211], v[168:171]
	v_mfma_f32_16x16x32_bf16 v[172:175], v[232:235], v[208:211], v[172:175]
	v_mfma_f32_16x16x32_bf16 v[132:135], v[236:239], v[208:211], v[132:135]
	v_mfma_f32_16x16x32_bf16 v[160:163], v[224:227], v[212:215], v[160:163]
	v_mfma_f32_16x16x32_bf16 v[188:191], v[228:231], v[212:215], v[188:191]
	v_mfma_f32_16x16x32_bf16 v[192:195], v[232:235], v[212:215], v[192:195]
	v_mfma_f32_16x16x32_bf16 v[136:139], v[236:239], v[212:215], v[136:139]
	v_mfma_f32_16x16x32_bf16 v[196:199], v[224:227], v[216:219], v[196:199]
	v_mfma_f32_16x16x32_bf16 v[200:203], v[228:231], v[216:219], v[200:203]
	v_mfma_f32_16x16x32_bf16 v[204:207], v[232:235], v[216:219], v[204:207]
	v_mfma_f32_16x16x32_bf16 v[140:143], v[236:239], v[216:219], v[140:143]
	v_mfma_f32_16x16x32_bf16 v[148:151], v[224:227], v[220:223], v[148:151]
	v_mfma_f32_16x16x32_bf16 v[152:155], v[228:231], v[220:223], v[152:155]
	v_mfma_f32_16x16x32_bf16 v[156:159], v[232:235], v[220:223], v[156:159]
	v_mfma_f32_16x16x32_bf16 v[144:147], v[236:239], v[220:223], v[144:147]
	ds_read_b128 v[36:39], v127
	ds_read_b128 v[40:43], v127 offset:2048
	ds_read_b128 v[44:47], v127 offset:4096
	ds_read_b128 v[48:51], v127 offset:6144
	ds_read_b128 v[208:211], v128 offset:32768
	ds_read_b128 v[212:215], v128 offset:34816
	ds_read_b128 v[216:219], v128 offset:36864
	ds_read_b128 v[220:223], v128 offset:38912
	s_waitcnt lgkmcnt(3)
	v_mfma_f32_16x16x32_bf16 v[164:167], v[208:211], v[36:39], v[164:167]
	s_waitcnt lgkmcnt(2)
	v_mfma_f32_16x16x32_bf16 v[168:171], v[212:215], v[36:39], v[168:171]
	s_waitcnt lgkmcnt(1)
	v_mfma_f32_16x16x32_bf16 v[172:175], v[216:219], v[36:39], v[172:175]
	s_waitcnt lgkmcnt(0)
	v_mfma_f32_16x16x32_bf16 v[36:39], v[220:223], v[36:39], v[132:135]
	v_mfma_f32_16x16x32_bf16 v[132:135], v[208:211], v[40:43], v[160:163]
	v_mfma_f32_16x16x32_bf16 v[160:163], v[212:215], v[40:43], v[188:191]
	v_mfma_f32_16x16x32_bf16 v[188:191], v[216:219], v[40:43], v[192:195]
	v_mfma_f32_16x16x32_bf16 v[40:43], v[220:223], v[40:43], v[136:139]
	v_mfma_f32_16x16x32_bf16 v[136:139], v[208:211], v[44:47], v[196:199]
	v_mfma_f32_16x16x32_bf16 v[192:195], v[212:215], v[44:47], v[200:203]
	v_mfma_f32_16x16x32_bf16 v[196:199], v[216:219], v[44:47], v[204:207]
	v_mfma_f32_16x16x32_bf16 v[44:47], v[220:223], v[44:47], v[140:143]
	v_mfma_f32_16x16x32_bf16 v[140:143], v[208:211], v[48:51], v[148:151]
	v_mfma_f32_16x16x32_bf16 v[148:151], v[212:215], v[48:51], v[152:155]
	v_mfma_f32_16x16x32_bf16 v[152:155], v[216:219], v[48:51], v[156:159]
	v_mfma_f32_16x16x32_bf16 v[48:51], v[220:223], v[48:51], v[144:147]
	s_nop 2
	ds_read_b128 v[144:147], v129
	ds_read_b128 v[156:159], v129 offset:2048
	ds_read_b128 v[200:203], v129 offset:4096
	ds_read_b128 v[204:207], v129 offset:6144
	ds_read_b128 v[208:211], v130 offset:32768
	ds_read_b128 v[212:215], v130 offset:34816
	ds_read_b128 v[216:219], v130 offset:36864
	ds_read_b128 v[220:223], v130 offset:38912
	s_waitcnt vmcnt(7)
	ds_write_b128 v126, v[4:7] offset:16384
	s_waitcnt vmcnt(6)
	ds_write_b128 v126, v[8:11] offset:49152
	s_waitcnt vmcnt(5)
	ds_write_b128 v126, v[12:15] offset:20480
	s_waitcnt vmcnt(4)
	ds_write_b128 v126, v[16:19] offset:53248
	s_waitcnt vmcnt(3)
	ds_write_b128 v126, v[20:23] offset:24576
	s_waitcnt vmcnt(2)
	ds_write_b128 v126, v[24:27] offset:57344
	s_waitcnt vmcnt(1)
	ds_write_b128 v126, v[28:31] offset:28672
	s_waitcnt vmcnt(0)
	ds_write_b128 v126, v[32:35] offset:61440
	s_waitcnt lgkmcnt(0)
	s_barrier
; __device__ __forceinline__ float bflo(unsigned u) { return __uint_as_float(u << 16); }
; __device__ __forceinline__ float bfhi(unsigned u) { return __uint_as_float(u & 0xffff0000u); }
; __device__ __forceinline__ float sigmoidf_(float x) { return frcp_(1.f + __expf(-x)); }
; __device__ __forceinline__ void phase_gemm_merge(const Params& p, char* smem) {
;     ...
; #pragma unroll
;       for (int i = 0; i < 4; ++i) {
;         const int m = mt * 128 + wm * 64 + i * 16 + (lane & 15);
; #pragma unroll
;         for (int j = 0; j < 4; ++j) {
;           const int n = nt * 128 + wn * 64 + j * 16 + (lane >> 4) * 4;
;           const uint2 gz = *(const uint2*)(POST + (size_t)m * POST_W + QC_GATE + b * 1024 + n);
;           outv[i][j][0] += sigmoidf_(bflo(gz.x)) * acc[i][j][0];
;           outv[i][j][1] += sigmoidf_(bfhi(gz.x)) * acc[i][j][1];
;           outv[i][j][2] += sigmoidf_(bflo(gz.y)) * acc[i][j][2];
;           outv[i][j][3] += sigmoidf_(bfhi(gz.y)) * acc[i][j][3];
;         }
;       }
	ds_read_b128 v[4:7], v127 offset:16384
	ds_read_b128 v[8:11], v127 offset:18432
	ds_read_b128 v[12:15], v127 offset:20480
	ds_read_b128 v[16:19], v127 offset:22528
	ds_read_b128 v[20:23], v128 offset:49152
	ds_read_b128 v[24:27], v128 offset:51200
	ds_read_b128 v[28:31], v128 offset:53248
	ds_read_b128 v[32:35], v128 offset:55296
	v_mfma_f32_16x16x32_bf16 v[164:167], v[208:211], v[144:147], v[164:167]
	v_mfma_f32_16x16x32_bf16 v[168:171], v[212:215], v[144:147], v[168:171]
	v_mfma_f32_16x16x32_bf16 v[172:175], v[216:219], v[144:147], v[172:175]
	v_mfma_f32_16x16x32_bf16 v[36:39], v[220:223], v[144:147], v[36:39]
	v_mfma_f32_16x16x32_bf16 v[132:135], v[208:211], v[156:159], v[132:135]
	v_mfma_f32_16x16x32_bf16 v[144:147], v[212:215], v[156:159], v[160:163]
	v_mfma_f32_16x16x32_bf16 v[160:163], v[216:219], v[156:159], v[188:191]
	v_mfma_f32_16x16x32_bf16 v[136:139], v[208:211], v[200:203], v[136:139]
	v_mfma_f32_16x16x32_bf16 v[188:191], v[216:219], v[200:203], v[196:199]
	v_mfma_f32_16x16x32_bf16 v[140:143], v[208:211], v[204:207], v[140:143]
	v_mfma_f32_16x16x32_bf16 v[148:151], v[212:215], v[204:207], v[148:151]
	v_mfma_f32_16x16x32_bf16 v[152:155], v[216:219], v[204:207], v[152:155]
	v_mfma_f32_16x16x32_bf16 v[48:51], v[220:223], v[204:207], v[48:51]
	v_mfma_f32_16x16x32_bf16 v[40:43], v[220:223], v[156:159], v[40:43]
	v_mfma_f32_16x16x32_bf16 v[156:159], v[212:215], v[200:203], v[192:195]
	v_mfma_f32_16x16x32_bf16 v[44:47], v[220:223], v[200:203], v[44:47]
	s_waitcnt lgkmcnt(3)
	v_mfma_f32_16x16x32_bf16 v[164:167], v[20:23], v[4:7], v[164:167]
	s_waitcnt lgkmcnt(2)
	v_mfma_f32_16x16x32_bf16 v[168:171], v[24:27], v[4:7], v[168:171]
	s_waitcnt lgkmcnt(1)
	v_mfma_f32_16x16x32_bf16 v[172:175], v[28:31], v[4:7], v[172:175]
	s_waitcnt lgkmcnt(0)
	v_mfma_f32_16x16x32_bf16 v[4:7], v[32:35], v[4:7], v[36:39]
	v_mfma_f32_16x16x32_bf16 v[36:39], v[20:23], v[8:11], v[132:135]
	v_mfma_f32_16x16x32_bf16 v[132:135], v[24:27], v[8:11], v[144:147]
	v_mfma_f32_16x16x32_bf16 v[144:147], v[28:31], v[8:11], v[160:163]
	v_mfma_f32_16x16x32_bf16 v[136:139], v[20:23], v[12:15], v[136:139]
	v_mfma_f32_16x16x32_bf16 v[160:163], v[28:31], v[12:15], v[188:191]
	v_mfma_f32_16x16x32_bf16 v[140:143], v[20:23], v[16:19], v[140:143]
	v_mfma_f32_16x16x32_bf16 v[148:151], v[24:27], v[16:19], v[148:151]
	v_mfma_f32_16x16x32_bf16 v[152:155], v[28:31], v[16:19], v[152:155]
	v_mfma_f32_16x16x32_bf16 v[188:191], v[32:35], v[16:19], v[48:51]
	ds_read_b128 v[16:19], v129 offset:16384
	ds_read_b128 v[20:23], v129 offset:18432
	ds_read_b128 v[192:195], v129 offset:20480
	ds_read_b128 v[126:129], v129 offset:22528
	ds_read_b128 v[196:199], v130 offset:49152
	ds_read_b128 v[200:203], v130 offset:51200
	ds_read_b128 v[204:207], v130 offset:53248
	ds_read_b128 v[208:211], v130 offset:55296
	s_waitcnt lgkmcnt(0)
	s_barrier
	v_mfma_f32_16x16x32_bf16 v[8:11], v[32:35], v[8:11], v[40:43]
	v_mfma_f32_16x16x32_bf16 v[156:159], v[24:27], v[12:15], v[156:159]
	v_mfma_f32_16x16x32_bf16 v[12:15], v[32:35], v[12:15], v[44:47]
	v_mfma_f32_16x16x32_bf16 v[164:167], v[196:199], v[16:19], v[164:167]
	v_mfma_f32_16x16x32_bf16 v[168:171], v[200:203], v[16:19], v[168:171]
	v_mfma_f32_16x16x32_bf16 v[172:175], v[204:207], v[16:19], v[172:175]
	v_mfma_f32_16x16x32_bf16 v[212:215], v[208:211], v[16:19], v[4:7]
	v_mfma_f32_16x16x32_bf16 v[48:51], v[196:199], v[20:23], v[36:39]
	v_mfma_f32_16x16x32_bf16 v[44:47], v[200:203], v[20:23], v[132:135]
	v_mfma_f32_16x16x32_bf16 v[40:43], v[204:207], v[20:23], v[144:147]
	s_nop 1
	v_mov_b32_e32 v133, v166
	v_mov_b32_e32 v166, v165
	v_mov_b32_e32 v132, v164
	v_mfma_f32_16x16x32_bf16 v[36:39], v[208:211], v[20:23], v[8:11]
	v_mfma_f32_16x16x32_bf16 v[20:23], v[208:211], v[192:195], v[12:15]
	v_mfma_f32_16x16x32_bf16 v[16:19], v[196:199], v[126:129], v[140:143]
	v_mfma_f32_16x16x32_bf16 v[12:15], v[200:203], v[126:129], v[148:151]
	v_mfma_f32_16x16x32_bf16 v[8:11], v[204:207], v[126:129], v[152:155]
	v_mfma_f32_16x16x32_bf16 v[4:7], v[208:211], v[126:129], v[188:191]
	v_lshl_add_u64 v[126:127], s[10:11], 0, v[110:111]
	v_add_co_u32_e32 v126, vcc, s59, v126
	v_mfma_f32_16x16x32_bf16 v[32:35], v[196:199], v[192:195], v[136:139]
	s_nop 0
	v_addc_co_u32_e32 v127, vcc, 0, v127, vcc
	global_load_dwordx2 v[128:129], v[126:127], off offset:3072
	v_mfma_f32_16x16x32_bf16 v[28:31], v[200:203], v[192:195], v[156:159]
	v_lshl_add_u64 v[110:111], v[110:111], 0, s[38:39]
	s_waitcnt vmcnt(0)
	v_lshlrev_b32_e32 v130, 16, v128
	v_and_b32_e32 v128, 0xffff0000, v128
	v_lshlrev_b32_e32 v131, 16, v129
	v_and_b32_e32 v129, 0xffff0000, v129
	v_mul_f32_e32 v128, 0xbfb8aa3b, v128
	v_mul_f32_e32 v129, 0xbfb8aa3b, v129
	v_exp_f32_e32 v128, v128
	v_exp_f32_e32 v129, v129
	v_mul_f32_e32 v130, 0xbfb8aa3b, v130
	v_mul_f32_e32 v131, 0xbfb8aa3b, v131
	v_add_f32_e32 v128, 1.0, v128
	v_add_f32_e32 v129, 1.0, v129
	v_rcp_f32_e32 v128, v128
	v_rcp_f32_e32 v129, v129
	v_exp_f32_e32 v130, v130
	v_exp_f32_e32 v131, v131
	v_mfma_f32_16x16x32_bf16 v[24:27], v[204:207], v[192:195], v[160:163]
	v_fma_f32 v118, v166, v128, v118
	v_fma_f32 v119, v167, v129, v119
	global_load_dwordx2 v[128:129], v[126:127], off offset:3104
	v_add_f32_e32 v130, 1.0, v130
	v_add_f32_e32 v131, 1.0, v131
	v_rcp_f32_e32 v130, v130
	v_rcp_f32_e32 v131, v131
	s_nop 0
	v_pk_fma_f32 v[120:121], v[132:133], v[130:131], v[120:121]
	v_mov_b32_e32 v133, v170
	v_mov_b32_e32 v170, v169
	v_mov_b32_e32 v132, v168
	s_waitcnt vmcnt(0)
; __device__ __forceinline__ float bflo(unsigned u) { return __uint_as_float(u << 16); }
; __device__ __forceinline__ float bfhi(unsigned u) { return __uint_as_float(u & 0xffff0000u); }
; __device__ __forceinline__ float sigmoidf_(float x) { return frcp_(1.f + __expf(-x)); }
; __device__ __forceinline__ void phase_gemm_merge(const Params& p, char* smem) {
;     ...
; #pragma unroll
;       for (int i = 0; i < 4; ++i) {
;         const int m = mt * 128 + wm * 64 + i * 16 + (lane & 15);
; #pragma unroll
;         for (int j = 0; j < 4; ++j) {
;           const int n = nt * 128 + wn * 64 + j * 16 + (lane >> 4) * 4;
;           const uint2 gz = *(const uint2*)(POST + (size_t)m * POST_W + QC_GATE + b * 1024 + n);
;           outv[i][j][0] += sigmoidf_(bflo(gz.x)) * acc[i][j][0];
;           outv[i][j][1] += sigmoidf_(bfhi(gz.x)) * acc[i][j][1];
;           outv[i][j][2] += sigmoidf_(bflo(gz.y)) * acc[i][j][2];
;           outv[i][j][3] += sigmoidf_(bfhi(gz.y)) * acc[i][j][3];
;         }
;       }
	v_lshlrev_b32_e32 v130, 16, v128
	v_and_b32_e32 v128, 0xffff0000, v128
	v_lshlrev_b32_e32 v131, 16, v129
	v_and_b32_e32 v129, 0xffff0000, v129
	v_mul_f32_e32 v128, 0xbfb8aa3b, v128
	v_mul_f32_e32 v129, 0xbfb8aa3b, v129
	v_exp_f32_e32 v128, v128
	v_exp_f32_e32 v129, v129
	v_mul_f32_e32 v130, 0xbfb8aa3b, v130
	v_mul_f32_e32 v131, 0xbfb8aa3b, v131
	v_add_f32_e32 v128, 1.0, v128
	v_add_f32_e32 v129, 1.0, v129
	v_rcp_f32_e32 v128, v128
	v_rcp_f32_e32 v129, v129
	v_exp_f32_e32 v130, v130
	v_exp_f32_e32 v131, v131
	v_pk_fma_f32 v[114:115], v[170:171], v[128:129], v[114:115]
	global_load_dwordx2 v[128:129], v[126:127], off offset:3136
	v_add_f32_e32 v130, 1.0, v130
	global_load_dwordx2 v[126:127], v[126:127], off offset:3168
	v_add_f32_e32 v131, 1.0, v131
	v_rcp_f32_e32 v130, v130
	v_rcp_f32_e32 v131, v131
	s_nop 0
	v_pk_fma_f32 v[116:117], v[132:133], v[130:131], v[116:117]
	v_mov_b32_e32 v133, v174
	v_mov_b32_e32 v174, v173
	v_mov_b32_e32 v132, v172
	s_waitcnt vmcnt(1)
	v_lshlrev_b32_e32 v130, 16, v128
	v_and_b32_e32 v128, 0xffff0000, v128
	v_lshlrev_b32_e32 v131, 16, v129
	v_and_b32_e32 v129, 0xffff0000, v129
	v_mul_f32_e32 v128, 0xbfb8aa3b, v128
	v_mul_f32_e32 v129, 0xbfb8aa3b, v129
	v_exp_f32_e32 v128, v128
	v_exp_f32_e32 v129, v129
	v_mul_f32_e32 v130, 0xbfb8aa3b, v130
	v_mul_f32_e32 v131, 0xbfb8aa3b, v131
	v_add_f32_e32 v128, 1.0, v128
	v_add_f32_e32 v129, 1.0, v129
	v_rcp_f32_e32 v128, v128
	v_rcp_f32_e32 v129, v129
	v_exp_f32_e32 v130, v130
	v_exp_f32_e32 v131, v131
	v_pk_fma_f32 v[108:109], v[174:175], v[128:129], v[108:109]
	s_waitcnt vmcnt(0)
	v_lshlrev_b32_e32 v128, 16, v126
	v_and_b32_e32 v126, 0xffff0000, v126
	v_lshlrev_b32_e32 v129, 16, v127
	v_and_b32_e32 v127, 0xffff0000, v127
	v_mul_f32_e32 v126, 0xbfb8aa3b, v126
	v_mul_f32_e32 v127, 0xbfb8aa3b, v127
	v_exp_f32_e32 v126, v126
	v_exp_f32_e32 v127, v127
	v_mul_f32_e32 v128, 0xbfb8aa3b, v128
	v_mul_f32_e32 v129, 0xbfb8aa3b, v129
	v_add_f32_e32 v130, 1.0, v130
	v_add_f32_e32 v131, 1.0, v131
	v_exp_f32_e32 v128, v128
	v_exp_f32_e32 v129, v129
	v_rcp_f32_e32 v130, v130
	v_rcp_f32_e32 v131, v131
	v_add_f32_e32 v126, 1.0, v126
	v_add_f32_e32 v127, 1.0, v127
	v_rcp_f32_e32 v126, v126
	v_rcp_f32_e32 v127, v127
	v_add_f32_e32 v128, 1.0, v128
	v_add_f32_e32 v129, 1.0, v129
	v_pk_fma_f32 v[112:113], v[132:133], v[130:131], v[112:113]
	v_rcp_f32_e32 v128, v128
	v_rcp_f32_e32 v129, v129
	v_mov_b32_e32 v131, v214
	v_mov_b32_e32 v214, v213
	v_pk_fma_f32 v[98:99], v[214:215], v[126:127], v[98:99]
	v_lshl_add_u64 v[126:127], s[10:11], 0, v[106:107]
	v_add_co_u32_e32 v126, vcc, s59, v126
	v_mov_b32_e32 v130, v212
	s_nop 0
	v_addc_co_u32_e32 v127, vcc, 0, v127, vcc
	v_pk_fma_f32 v[100:101], v[130:131], v[128:129], v[100:101]
	global_load_dwordx2 v[128:129], v[126:127], off offset:3072
	v_mov_b32_e32 v132, v48
	v_mov_b32_e32 v133, v50
	v_mov_b32_e32 v50, v49
	global_load_dwordx2 v[48:49], v[126:127], off offset:3104
	v_lshl_add_u64 v[106:107], v[106:107], 0, s[38:39]
	s_waitcnt vmcnt(1)
	v_lshlrev_b32_e32 v130, 16, v128
	v_and_b32_e32 v128, 0xffff0000, v128
	v_lshlrev_b32_e32 v131, 16, v129
	v_and_b32_e32 v129, 0xffff0000, v129
	v_mul_f32_e32 v128, 0xbfb8aa3b, v128
	v_mul_f32_e32 v129, 0xbfb8aa3b, v129
	v_exp_f32_e32 v128, v128
	v_exp_f32_e32 v129, v129
	v_mul_f32_e32 v130, 0xbfb8aa3b, v130
	v_mul_f32_e32 v131, 0xbfb8aa3b, v131
	v_add_f32_e32 v128, 1.0, v128
	v_add_f32_e32 v129, 1.0, v129
	v_rcp_f32_e32 v128, v128
	v_rcp_f32_e32 v129, v129
	v_exp_f32_e32 v130, v130
	v_exp_f32_e32 v131, v131
	v_pk_fma_f32 v[94:95], v[50:51], v[128:129], v[94:95]
	s_waitcnt vmcnt(0)
	v_lshlrev_b32_e32 v50, 16, v48
	v_and_b32_e32 v48, 0xffff0000, v48
	v_lshlrev_b32_e32 v51, 16, v49
	v_and_b32_e32 v49, 0xffff0000, v49
	v_mov_b32_e32 v128, v44
	v_mov_b32_e32 v129, v46
	v_mov_b32_e32 v46, v45
	global_load_dwordx2 v[44:45], v[126:127], off offset:3136
	v_mul_f32_e32 v48, 0xbfb8aa3b, v48
	v_mul_f32_e32 v49, 0xbfb8aa3b, v49
	v_exp_f32_e32 v48, v48
	v_exp_f32_e32 v49, v49
	v_mul_f32_e32 v50, 0xbfb8aa3b, v50
	v_mul_f32_e32 v51, 0xbfb8aa3b, v51
	v_add_f32_e32 v48, 1.0, v48
	v_add_f32_e32 v49, 1.0, v49
	v_rcp_f32_e32 v48, v48
	v_rcp_f32_e32 v49, v49
	v_exp_f32_e32 v50, v50
	v_exp_f32_e32 v51, v51
	v_add_f32_e32 v130, 1.0, v130
	v_pk_fma_f32 v[90:91], v[46:47], v[48:49], v[90:91]
	v_mov_b32_e32 v48, v40
	v_mov_b32_e32 v49, v42
	v_mov_b32_e32 v42, v41
	global_load_dwordx2 v[40:41], v[126:127], off offset:3168
	v_add_f32_e32 v131, 1.0, v131
	v_add_f32_e32 v50, 1.0, v50
	v_add_f32_e32 v51, 1.0, v51
	v_rcp_f32_e32 v130, v130
	v_rcp_f32_e32 v131, v131
	v_rcp_f32_e32 v50, v50
	v_rcp_f32_e32 v51, v51
	v_pk_fma_f32 v[96:97], v[132:133], v[130:131], v[96:97]
	v_pk_fma_f32 v[92:93], v[128:129], v[50:51], v[92:93]
	s_waitcnt vmcnt(1)
	v_lshlrev_b32_e32 v46, 16, v44
	v_and_b32_e32 v44, 0xffff0000, v44
	v_lshlrev_b32_e32 v47, 16, v45
	v_and_b32_e32 v45, 0xffff0000, v45
	v_mul_f32_e32 v44, 0xbfb8aa3b, v44
	v_mul_f32_e32 v45, 0xbfb8aa3b, v45
	v_exp_f32_e32 v44, v44
	v_exp_f32_e32 v45, v45
	v_mul_f32_e32 v46, 0xbfb8aa3b, v46
	v_mul_f32_e32 v47, 0xbfb8aa3b, v47
	v_add_f32_e32 v44, 1.0, v44
	v_add_f32_e32 v45, 1.0, v45
	v_rcp_f32_e32 v44, v44
	v_rcp_f32_e32 v45, v45
	v_exp_f32_e32 v46, v46
	v_exp_f32_e32 v47, v47
	v_pk_fma_f32 v[86:87], v[42:43], v[44:45], v[86:87]
	s_waitcnt vmcnt(0)
; __device__ __forceinline__ float bflo(unsigned u) { return __uint_as_float(u << 16); }
; __device__ __forceinline__ float bfhi(unsigned u) { return __uint_as_float(u & 0xffff0000u); }
; __device__ __forceinline__ float sigmoidf_(float x) { return frcp_(1.f + __expf(-x)); }
; __device__ __forceinline__ void phase_gemm_merge(const Params& p, char* smem) {
;     ...
; #pragma unroll
;       for (int i = 0; i < 4; ++i) {
;         const int m = mt * 128 + wm * 64 + i * 16 + (lane & 15);
; #pragma unroll
;         for (int j = 0; j < 4; ++j) {
;           const int n = nt * 128 + wn * 64 + j * 16 + (lane >> 4) * 4;
;           const uint2 gz = *(const uint2*)(POST + (size_t)m * POST_W + QC_GATE + b * 1024 + n);
;           outv[i][j][0] += sigmoidf_(bflo(gz.x)) * acc[i][j][0];
;           outv[i][j][1] += sigmoidf_(bfhi(gz.x)) * acc[i][j][1];
;           outv[i][j][2] += sigmoidf_(bflo(gz.y)) * acc[i][j][2];
;           outv[i][j][3] += sigmoidf_(bfhi(gz.y)) * acc[i][j][3];
;         }
;       }
	v_lshlrev_b32_e32 v42, 16, v40
	v_and_b32_e32 v40, 0xffff0000, v40
	v_lshlrev_b32_e32 v43, 16, v41
	v_and_b32_e32 v41, 0xffff0000, v41
	v_mul_f32_e32 v40, 0xbfb8aa3b, v40
	v_mul_f32_e32 v41, 0xbfb8aa3b, v41
	v_exp_f32_e32 v40, v40
	v_exp_f32_e32 v41, v41
	v_mov_b32_e32 v44, v36
	v_mov_b32_e32 v45, v38
	v_add_f32_e32 v40, 1.0, v40
	v_add_f32_e32 v41, 1.0, v41
	v_rcp_f32_e32 v40, v40
	v_rcp_f32_e32 v41, v41
	v_mov_b32_e32 v38, v37
	v_lshl_add_u64 v[36:37], s[10:11], 0, v[104:105]
	v_add_co_u32_e32 v36, vcc, s59, v36
	v_pk_fma_f32 v[82:83], v[38:39], v[40:41], v[82:83]
	s_nop 0
	v_addc_co_u32_e32 v37, vcc, 0, v37, vcc
	global_load_dwordx2 v[38:39], v[36:37], off offset:3072
	v_mul_f32_e32 v42, 0xbfb8aa3b, v42
	v_mul_f32_e32 v43, 0xbfb8aa3b, v43
	v_exp_f32_e32 v42, v42
	v_exp_f32_e32 v43, v43
	v_add_f32_e32 v46, 1.0, v46
	v_add_f32_e32 v47, 1.0, v47
	v_add_f32_e32 v42, 1.0, v42
	v_add_f32_e32 v43, 1.0, v43
	v_rcp_f32_e32 v42, v42
	v_rcp_f32_e32 v43, v43
	v_rcp_f32_e32 v46, v46
	v_rcp_f32_e32 v47, v47
	v_lshl_add_u64 v[104:105], v[104:105], 0, s[38:39]
	v_pk_fma_f32 v[84:85], v[44:45], v[42:43], v[84:85]
	v_mov_b32_e32 v42, v32
	v_mov_b32_e32 v43, v34
	v_mov_b32_e32 v34, v33
	global_load_dwordx2 v[32:33], v[36:37], off offset:3104
	v_pk_fma_f32 v[88:89], v[48:49], v[46:47], v[88:89]
	s_waitcnt vmcnt(1)
	v_lshlrev_b32_e32 v40, 16, v38
	v_and_b32_e32 v38, 0xffff0000, v38
	v_lshlrev_b32_e32 v41, 16, v39
	v_and_b32_e32 v39, 0xffff0000, v39
	v_mul_f32_e32 v38, 0xbfb8aa3b, v38
	v_mul_f32_e32 v39, 0xbfb8aa3b, v39
	v_exp_f32_e32 v38, v38
	v_exp_f32_e32 v39, v39
	v_mul_f32_e32 v40, 0xbfb8aa3b, v40
	v_mul_f32_e32 v41, 0xbfb8aa3b, v41
	v_add_f32_e32 v38, 1.0, v38
	v_add_f32_e32 v39, 1.0, v39
	v_rcp_f32_e32 v38, v38
	v_rcp_f32_e32 v39, v39
	v_exp_f32_e32 v40, v40
	v_exp_f32_e32 v41, v41
	v_pk_fma_f32 v[78:79], v[34:35], v[38:39], v[78:79]
	s_waitcnt vmcnt(0)
	v_lshlrev_b32_e32 v34, 16, v32
	v_and_b32_e32 v32, 0xffff0000, v32
	v_lshlrev_b32_e32 v35, 16, v33
	v_and_b32_e32 v33, 0xffff0000, v33
	v_mov_b32_e32 v38, v28
	v_mov_b32_e32 v39, v30
	v_mov_b32_e32 v30, v29
	global_load_dwordx2 v[28:29], v[36:37], off offset:3136
	v_mul_f32_e32 v32, 0xbfb8aa3b, v32
	v_mul_f32_e32 v33, 0xbfb8aa3b, v33
	v_exp_f32_e32 v32, v32
	v_exp_f32_e32 v33, v33
	v_mul_f32_e32 v34, 0xbfb8aa3b, v34
	v_mul_f32_e32 v35, 0xbfb8aa3b, v35
	v_add_f32_e32 v32, 1.0, v32
	v_add_f32_e32 v33, 1.0, v33
	v_rcp_f32_e32 v32, v32
	v_rcp_f32_e32 v33, v33
	v_exp_f32_e32 v34, v34
	v_exp_f32_e32 v35, v35
	v_add_f32_e32 v40, 1.0, v40
	v_pk_fma_f32 v[74:75], v[30:31], v[32:33], v[74:75]
	v_mov_b32_e32 v32, v24
	v_mov_b32_e32 v33, v26
	v_mov_b32_e32 v26, v25
	global_load_dwordx2 v[24:25], v[36:37], off offset:3168
	v_add_f32_e32 v41, 1.0, v41
	v_add_f32_e32 v34, 1.0, v34
	v_add_f32_e32 v35, 1.0, v35
	v_rcp_f32_e32 v40, v40
	v_rcp_f32_e32 v41, v41
	v_rcp_f32_e32 v34, v34
	v_rcp_f32_e32 v35, v35
	v_pk_fma_f32 v[80:81], v[42:43], v[40:41], v[80:81]
	v_pk_fma_f32 v[76:77], v[38:39], v[34:35], v[76:77]
	s_waitcnt vmcnt(1)
	v_lshlrev_b32_e32 v30, 16, v28
	v_and_b32_e32 v28, 0xffff0000, v28
	v_lshlrev_b32_e32 v31, 16, v29
	v_and_b32_e32 v29, 0xffff0000, v29
	v_mul_f32_e32 v28, 0xbfb8aa3b, v28
	v_mul_f32_e32 v29, 0xbfb8aa3b, v29
	v_exp_f32_e32 v28, v28
	v_exp_f32_e32 v29, v29
	v_mul_f32_e32 v30, 0xbfb8aa3b, v30
	v_mul_f32_e32 v31, 0xbfb8aa3b, v31
	v_add_f32_e32 v28, 1.0, v28
	v_add_f32_e32 v29, 1.0, v29
	v_rcp_f32_e32 v28, v28
	v_rcp_f32_e32 v29, v29
	v_exp_f32_e32 v30, v30
	v_exp_f32_e32 v31, v31
	v_pk_fma_f32 v[70:71], v[26:27], v[28:29], v[70:71]
	s_waitcnt vmcnt(0)
	v_lshlrev_b32_e32 v26, 16, v24
	v_and_b32_e32 v24, 0xffff0000, v24
	v_lshlrev_b32_e32 v27, 16, v25
	v_and_b32_e32 v25, 0xffff0000, v25
	v_mul_f32_e32 v24, 0xbfb8aa3b, v24
	v_mul_f32_e32 v25, 0xbfb8aa3b, v25
	v_exp_f32_e32 v24, v24
	v_exp_f32_e32 v25, v25
	v_mov_b32_e32 v28, v20
	v_mov_b32_e32 v29, v22
	v_add_f32_e32 v24, 1.0, v24
	v_add_f32_e32 v25, 1.0, v25
	v_rcp_f32_e32 v24, v24
	v_rcp_f32_e32 v25, v25
	v_mov_b32_e32 v22, v21
	v_lshl_add_u64 v[20:21], s[10:11], 0, v[102:103]
	v_add_co_u32_e32 v20, vcc, s59, v20
	v_pk_fma_f32 v[66:67], v[22:23], v[24:25], v[66:67]
	s_nop 0
	v_addc_co_u32_e32 v21, vcc, 0, v21, vcc
	global_load_dwordx2 v[22:23], v[20:21], off offset:3072
	v_mul_f32_e32 v26, 0xbfb8aa3b, v26
	v_mul_f32_e32 v27, 0xbfb8aa3b, v27
	v_exp_f32_e32 v26, v26
	v_exp_f32_e32 v27, v27
	v_add_f32_e32 v30, 1.0, v30
	v_add_f32_e32 v31, 1.0, v31
	v_add_f32_e32 v26, 1.0, v26
	v_add_f32_e32 v27, 1.0, v27
	v_rcp_f32_e32 v26, v26
	v_rcp_f32_e32 v27, v27
	v_rcp_f32_e32 v30, v30
	v_rcp_f32_e32 v31, v31
	v_lshl_add_u64 v[102:103], v[102:103], 0, s[38:39]
	v_pk_fma_f32 v[68:69], v[28:29], v[26:27], v[68:69]
	v_mov_b32_e32 v26, v16
	v_mov_b32_e32 v27, v18
	v_mov_b32_e32 v18, v17
	global_load_dwordx2 v[16:17], v[20:21], off offset:3104
	v_pk_fma_f32 v[72:73], v[32:33], v[30:31], v[72:73]
	s_waitcnt vmcnt(1)
	v_lshlrev_b32_e32 v24, 16, v22
	v_and_b32_e32 v22, 0xffff0000, v22
	v_lshlrev_b32_e32 v25, 16, v23
	v_and_b32_e32 v23, 0xffff0000, v23
	v_mul_f32_e32 v22, 0xbfb8aa3b, v22
	v_mul_f32_e32 v23, 0xbfb8aa3b, v23
	v_exp_f32_e32 v22, v22
	v_exp_f32_e32 v23, v23
	v_mul_f32_e32 v24, 0xbfb8aa3b, v24
	v_mul_f32_e32 v25, 0xbfb8aa3b, v25
	v_add_f32_e32 v22, 1.0, v22
	v_add_f32_e32 v23, 1.0, v23
	v_rcp_f32_e32 v22, v22
	v_rcp_f32_e32 v23, v23
	v_exp_f32_e32 v24, v24
	v_exp_f32_e32 v25, v25
	v_pk_fma_f32 v[62:63], v[18:19], v[22:23], v[62:63]
	s_waitcnt vmcnt(0)
; __device__ __forceinline__ unsigned pack2(float a, float b) { return (unsigned)f2bf(a) | ((unsigned)f2bf(b) << 16); }
; __device__ __forceinline__ float bflo(unsigned u) { return __uint_as_float(u << 16); }
; __device__ __forceinline__ float bfhi(unsigned u) { return __uint_as_float(u & 0xffff0000u); }
; __device__ __forceinline__ float sigmoidf_(float x) { return frcp_(1.f + __expf(-x)); }
; __device__ __forceinline__ void phase_gemm_merge(const Params& p, char* smem) {
;     ...
;           const uint2 gz = *(const uint2*)(POST + (size_t)m * POST_W + QC_GATE + b * 1024 + n);
;           outv[i][j][0] += sigmoidf_(bflo(gz.x)) * acc[i][j][0];
;           outv[i][j][1] += sigmoidf_(bfhi(gz.x)) * acc[i][j][1];
;           outv[i][j][2] += sigmoidf_(bflo(gz.y)) * acc[i][j][2];
;           outv[i][j][3] += sigmoidf_(bfhi(gz.y)) * acc[i][j][3];
;         }
;       }
;     }
; #pragma unroll
;     for (int i = 0; i < 4; ++i) {
;       const int m = mt * 128 + wm * 64 + i * 16 + (lane & 15);
; #pragma unroll
;       for (int j = 0; j < 4; ++j) {
;         const int n = nt * 128 + wn * 64 + j * 16 + (lane >> 4) * 4;
;         uint2 o;
;         o.x = pack2(outv[i][j][0], outv[i][j][1]);
;         o.y = pack2(outv[i][j][2], outv[i][j][3]);
;         *(uint2*)(MG + (size_t)m * 1024 + n) = o;
	v_lshlrev_b32_e32 v18, 16, v16
	v_and_b32_e32 v16, 0xffff0000, v16
	v_lshlrev_b32_e32 v19, 16, v17
	v_and_b32_e32 v17, 0xffff0000, v17
	v_mov_b32_e32 v22, v12
	v_mov_b32_e32 v23, v14
	v_mov_b32_e32 v14, v13
	global_load_dwordx2 v[12:13], v[20:21], off offset:3136
	v_mul_f32_e32 v16, 0xbfb8aa3b, v16
	v_mul_f32_e32 v17, 0xbfb8aa3b, v17
	v_exp_f32_e32 v16, v16
	v_exp_f32_e32 v17, v17
	v_mul_f32_e32 v18, 0xbfb8aa3b, v18
	v_mul_f32_e32 v19, 0xbfb8aa3b, v19
	v_add_f32_e32 v16, 1.0, v16
	v_add_f32_e32 v17, 1.0, v17
	v_rcp_f32_e32 v16, v16
	v_rcp_f32_e32 v17, v17
	v_exp_f32_e32 v18, v18
	v_exp_f32_e32 v19, v19
	v_add_f32_e32 v24, 1.0, v24
	v_pk_fma_f32 v[58:59], v[14:15], v[16:17], v[58:59]
	v_mov_b32_e32 v16, v8
	v_mov_b32_e32 v17, v10
	v_mov_b32_e32 v10, v9
	global_load_dwordx2 v[8:9], v[20:21], off offset:3168
	v_add_f32_e32 v25, 1.0, v25
	v_add_f32_e32 v18, 1.0, v18
	v_add_f32_e32 v19, 1.0, v19
	v_rcp_f32_e32 v24, v24
	v_rcp_f32_e32 v25, v25
	v_rcp_f32_e32 v18, v18
	v_rcp_f32_e32 v19, v19
	v_pk_fma_f32 v[64:65], v[26:27], v[24:25], v[64:65]
	v_pk_fma_f32 v[60:61], v[22:23], v[18:19], v[60:61]
	s_waitcnt vmcnt(1)
	v_lshlrev_b32_e32 v14, 16, v12
	v_and_b32_e32 v12, 0xffff0000, v12
	v_lshlrev_b32_e32 v15, 16, v13
	v_and_b32_e32 v13, 0xffff0000, v13
	v_mul_f32_e32 v12, 0xbfb8aa3b, v12
	v_mul_f32_e32 v13, 0xbfb8aa3b, v13
	v_exp_f32_e32 v12, v12
	v_exp_f32_e32 v13, v13
	v_mul_f32_e32 v14, 0xbfb8aa3b, v14
	v_mul_f32_e32 v15, 0xbfb8aa3b, v15
	v_add_f32_e32 v12, 1.0, v12
	v_add_f32_e32 v13, 1.0, v13
	v_rcp_f32_e32 v12, v12
	v_rcp_f32_e32 v13, v13
	v_exp_f32_e32 v14, v14
	v_exp_f32_e32 v15, v15
	v_pk_fma_f32 v[54:55], v[10:11], v[12:13], v[54:55]
	s_waitcnt vmcnt(0)
	v_lshlrev_b32_e32 v10, 16, v8
	v_and_b32_e32 v8, 0xffff0000, v8
	v_lshlrev_b32_e32 v11, 16, v9
	v_and_b32_e32 v9, 0xffff0000, v9
	v_mul_f32_e32 v10, 0xbfb8aa3b, v10
	v_mul_f32_e32 v8, 0xbfb8aa3b, v8
	v_mul_f32_e32 v11, 0xbfb8aa3b, v11
	v_mul_f32_e32 v9, 0xbfb8aa3b, v9
	v_exp_f32_e32 v10, v10
	v_exp_f32_e32 v8, v8
	v_exp_f32_e32 v11, v11
	v_exp_f32_e32 v9, v9
	v_add_f32_e32 v14, 1.0, v14
	v_add_f32_e32 v15, 1.0, v15
	v_add_f32_e32 v10, 1.0, v10
	v_add_f32_e32 v8, 1.0, v8
	v_add_f32_e32 v11, 1.0, v11
	v_add_f32_e32 v9, 1.0, v9
	v_rcp_f32_e32 v14, v14
	v_rcp_f32_e32 v15, v15
	v_rcp_f32_e32 v10, v10
	v_rcp_f32_e32 v8, v8
	v_rcp_f32_e32 v11, v11
	v_rcp_f32_e32 v9, v9
	v_mov_b32_e32 v12, v4
	v_mov_b32_e32 v13, v6
	v_mov_b32_e32 v6, v5
	v_pk_fma_f32 v[56:57], v[16:17], v[14:15], v[56:57]
	v_pk_fma_f32 v[0:1], v[12:13], v[10:11], v[0:1]
	v_pk_fma_f32 v[52:53], v[6:7], v[8:9], v[52:53]
	s_cbranch_scc0 .LBB0_21
	v_lshl_add_u32 v4, s27, 7, v2
	v_and_b32_sdwa v15, v120, v183 dst_sel:DWORD dst_unused:UNUSED_PAD src0_sel:WORD_1 src1_sel:DWORD
	v_or_b32_e32 v6, s12, v122
	v_ashrrev_i32_e32 v5, 31, v4
	v_readlane_b32 s12, v244, 7
	v_add3_u32 v16, v120, v15, s37
	v_and_b32_sdwa v15, v119, v183 dst_sel:DWORD dst_unused:UNUSED_PAD src0_sel:WORD_1 src1_sel:DWORD
	v_and_b32_sdwa v17, v118, v183 dst_sel:DWORD dst_unused:UNUSED_PAD src0_sel:WORD_1 src1_sel:DWORD
	v_or_b32_e32 v8, 48, v4
	v_ashrrev_i32_e32 v7, 31, v6
	v_or_b32_e32 v10, 16, v4
	v_or_b32_e32 v12, 32, v4
	v_lshlrev_b64 v[4:5], 11, v[4:5]
	v_readlane_b32 s13, v244, 8
	v_and_b32_sdwa v14, v121, v183 dst_sel:DWORD dst_unused:UNUSED_PAD src0_sel:WORD_1 src1_sel:DWORD
	v_add3_u32 v15, v119, v15, s37
	v_add3_u32 v17, v118, v17, s37
	v_lshl_add_u64 v[4:5], s[12:13], 0, v[4:5]
	v_lshlrev_b64 v[6:7], 1, v[6:7]
	v_add3_u32 v14, v121, v14, s37
	v_and_b32_e32 v15, 0xffff0000, v15
	v_and_b32_e32 v17, 0xffff0000, v17
	v_lshl_add_u64 v[4:5], v[4:5], 0, v[6:7]
	v_or_b32_sdwa v15, v15, v14 dst_sel:DWORD dst_unused:UNUSED_PAD src0_sel:DWORD src1_sel:WORD_1
	v_or_b32_sdwa v14, v17, v16 dst_sel:DWORD dst_unused:UNUSED_PAD src0_sel:DWORD src1_sel:WORD_1
	global_store_dwordx2 v[4:5], v[14:15], off
	v_and_b32_sdwa v15, v116, v183 dst_sel:DWORD dst_unused:UNUSED_PAD src0_sel:WORD_1 src1_sel:DWORD
	v_add3_u32 v16, v116, v15, s37
	v_and_b32_sdwa v15, v115, v183 dst_sel:DWORD dst_unused:UNUSED_PAD src0_sel:WORD_1 src1_sel:DWORD
	v_and_b32_sdwa v17, v114, v183 dst_sel:DWORD dst_unused:UNUSED_PAD src0_sel:WORD_1 src1_sel:DWORD
	v_and_b32_sdwa v14, v117, v183 dst_sel:DWORD dst_unused:UNUSED_PAD src0_sel:WORD_1 src1_sel:DWORD
	v_add3_u32 v15, v115, v15, s37
	v_add3_u32 v17, v114, v17, s37
	v_add3_u32 v14, v117, v14, s37
	v_and_b32_e32 v15, 0xffff0000, v15
	v_and_b32_e32 v17, 0xffff0000, v17
	v_or_b32_sdwa v15, v15, v14 dst_sel:DWORD dst_unused:UNUSED_PAD src0_sel:DWORD src1_sel:WORD_1
	v_or_b32_sdwa v14, v17, v16 dst_sel:DWORD dst_unused:UNUSED_PAD src0_sel:DWORD src1_sel:WORD_1
	global_store_dwordx2 v[4:5], v[14:15], off offset:32
	v_and_b32_sdwa v15, v112, v183 dst_sel:DWORD dst_unused:UNUSED_PAD src0_sel:WORD_1 src1_sel:DWORD
	v_add3_u32 v16, v112, v15, s37
	v_and_b32_sdwa v15, v109, v183 dst_sel:DWORD dst_unused:UNUSED_PAD src0_sel:WORD_1 src1_sel:DWORD
	v_and_b32_sdwa v17, v108, v183 dst_sel:DWORD dst_unused:UNUSED_PAD src0_sel:WORD_1 src1_sel:DWORD
	v_and_b32_sdwa v14, v113, v183 dst_sel:DWORD dst_unused:UNUSED_PAD src0_sel:WORD_1 src1_sel:DWORD
	v_add3_u32 v15, v109, v15, s37
	v_add3_u32 v17, v108, v17, s37
	v_add3_u32 v14, v113, v14, s37
	v_and_b32_e32 v15, 0xffff0000, v15
	v_and_b32_e32 v17, 0xffff0000, v17
	v_or_b32_sdwa v15, v15, v14 dst_sel:DWORD dst_unused:UNUSED_PAD src0_sel:DWORD src1_sel:WORD_1
	v_or_b32_sdwa v14, v17, v16 dst_sel:DWORD dst_unused:UNUSED_PAD src0_sel:DWORD src1_sel:WORD_1
	global_store_dwordx2 v[4:5], v[14:15], off offset:64
	v_and_b32_sdwa v15, v100, v183 dst_sel:DWORD dst_unused:UNUSED_PAD src0_sel:WORD_1 src1_sel:DWORD
	v_add3_u32 v16, v100, v15, s37
; __device__ __forceinline__ unsigned pack2(float a, float b) { return (unsigned)f2bf(a) | ((unsigned)f2bf(b) << 16); }
; __device__ __forceinline__ void phase_gemm_merge(const Params& p, char* smem) {
;     ...
; #pragma unroll
;     for (int i = 0; i < 4; ++i) {
;       const int m = mt * 128 + wm * 64 + i * 16 + (lane & 15);
; #pragma unroll
;       for (int j = 0; j < 4; ++j) {
;         const int n = nt * 128 + wn * 64 + j * 16 + (lane >> 4) * 4;
;         uint2 o;
;         o.x = pack2(outv[i][j][0], outv[i][j][1]);
;         o.y = pack2(outv[i][j][2], outv[i][j][3]);
;         *(uint2*)(MG + (size_t)m * 1024 + n) = o;
;       }
	v_and_b32_sdwa v15, v99, v183 dst_sel:DWORD dst_unused:UNUSED_PAD src0_sel:WORD_1 src1_sel:DWORD
	v_and_b32_sdwa v17, v98, v183 dst_sel:DWORD dst_unused:UNUSED_PAD src0_sel:WORD_1 src1_sel:DWORD
	v_and_b32_sdwa v14, v101, v183 dst_sel:DWORD dst_unused:UNUSED_PAD src0_sel:WORD_1 src1_sel:DWORD
	v_add3_u32 v15, v99, v15, s37
	v_add3_u32 v17, v98, v17, s37
	v_add3_u32 v14, v101, v14, s37
	v_and_b32_e32 v15, 0xffff0000, v15
	v_and_b32_e32 v17, 0xffff0000, v17
	v_ashrrev_i32_e32 v11, 31, v10
	v_or_b32_sdwa v15, v15, v14 dst_sel:DWORD dst_unused:UNUSED_PAD src0_sel:DWORD src1_sel:WORD_1
	v_or_b32_sdwa v14, v17, v16 dst_sel:DWORD dst_unused:UNUSED_PAD src0_sel:DWORD src1_sel:WORD_1
	global_store_dwordx2 v[4:5], v[14:15], off offset:96
	v_lshlrev_b64 v[4:5], 11, v[10:11]
	v_and_b32_sdwa v11, v96, v183 dst_sel:DWORD dst_unused:UNUSED_PAD src0_sel:WORD_1 src1_sel:DWORD
	v_add3_u32 v14, v96, v11, s37
	v_and_b32_sdwa v11, v95, v183 dst_sel:DWORD dst_unused:UNUSED_PAD src0_sel:WORD_1 src1_sel:DWORD
	v_and_b32_sdwa v15, v94, v183 dst_sel:DWORD dst_unused:UNUSED_PAD src0_sel:WORD_1 src1_sel:DWORD
	v_and_b32_sdwa v10, v97, v183 dst_sel:DWORD dst_unused:UNUSED_PAD src0_sel:WORD_1 src1_sel:DWORD
	v_add3_u32 v11, v95, v11, s37
	v_add3_u32 v15, v94, v15, s37
	v_lshl_add_u64 v[4:5], s[12:13], 0, v[4:5]
	v_add3_u32 v10, v97, v10, s37
	v_and_b32_e32 v11, 0xffff0000, v11
	v_and_b32_e32 v15, 0xffff0000, v15
	v_lshl_add_u64 v[4:5], v[4:5], 0, v[6:7]
	v_or_b32_sdwa v11, v11, v10 dst_sel:DWORD dst_unused:UNUSED_PAD src0_sel:DWORD src1_sel:WORD_1
	v_or_b32_sdwa v10, v15, v14 dst_sel:DWORD dst_unused:UNUSED_PAD src0_sel:DWORD src1_sel:WORD_1
	global_store_dwordx2 v[4:5], v[10:11], off
	v_and_b32_sdwa v11, v92, v183 dst_sel:DWORD dst_unused:UNUSED_PAD src0_sel:WORD_1 src1_sel:DWORD
	v_add3_u32 v14, v92, v11, s37
	v_and_b32_sdwa v11, v91, v183 dst_sel:DWORD dst_unused:UNUSED_PAD src0_sel:WORD_1 src1_sel:DWORD
	v_and_b32_sdwa v15, v90, v183 dst_sel:DWORD dst_unused:UNUSED_PAD src0_sel:WORD_1 src1_sel:DWORD
	v_and_b32_sdwa v10, v93, v183 dst_sel:DWORD dst_unused:UNUSED_PAD src0_sel:WORD_1 src1_sel:DWORD
	v_add3_u32 v11, v91, v11, s37
	v_add3_u32 v15, v90, v15, s37
	v_add3_u32 v10, v93, v10, s37
	v_and_b32_e32 v11, 0xffff0000, v11
	v_and_b32_e32 v15, 0xffff0000, v15
	v_or_b32_sdwa v11, v11, v10 dst_sel:DWORD dst_unused:UNUSED_PAD src0_sel:DWORD src1_sel:WORD_1
	v_or_b32_sdwa v10, v15, v14 dst_sel:DWORD dst_unused:UNUSED_PAD src0_sel:DWORD src1_sel:WORD_1
	global_store_dwordx2 v[4:5], v[10:11], off offset:32
	v_and_b32_sdwa v11, v88, v183 dst_sel:DWORD dst_unused:UNUSED_PAD src0_sel:WORD_1 src1_sel:DWORD
	v_add3_u32 v14, v88, v11, s37
	v_and_b32_sdwa v11, v87, v183 dst_sel:DWORD dst_unused:UNUSED_PAD src0_sel:WORD_1 src1_sel:DWORD
	v_and_b32_sdwa v15, v86, v183 dst_sel:DWORD dst_unused:UNUSED_PAD src0_sel:WORD_1 src1_sel:DWORD
	v_and_b32_sdwa v10, v89, v183 dst_sel:DWORD dst_unused:UNUSED_PAD src0_sel:WORD_1 src1_sel:DWORD
	v_add3_u32 v11, v87, v11, s37
	v_add3_u32 v15, v86, v15, s37
	v_add3_u32 v10, v89, v10, s37
	v_and_b32_e32 v11, 0xffff0000, v11
	v_and_b32_e32 v15, 0xffff0000, v15
	v_or_b32_sdwa v11, v11, v10 dst_sel:DWORD dst_unused:UNUSED_PAD src0_sel:DWORD src1_sel:WORD_1
	v_or_b32_sdwa v10, v15, v14 dst_sel:DWORD dst_unused:UNUSED_PAD src0_sel:DWORD src1_sel:WORD_1
	global_store_dwordx2 v[4:5], v[10:11], off offset:64
	v_and_b32_sdwa v11, v84, v183 dst_sel:DWORD dst_unused:UNUSED_PAD src0_sel:WORD_1 src1_sel:DWORD
	v_add3_u32 v14, v84, v11, s37
	v_and_b32_sdwa v11, v83, v183 dst_sel:DWORD dst_unused:UNUSED_PAD src0_sel:WORD_1 src1_sel:DWORD
	v_and_b32_sdwa v15, v82, v183 dst_sel:DWORD dst_unused:UNUSED_PAD src0_sel:WORD_1 src1_sel:DWORD
	v_and_b32_sdwa v10, v85, v183 dst_sel:DWORD dst_unused:UNUSED_PAD src0_sel:WORD_1 src1_sel:DWORD
	v_add3_u32 v11, v83, v11, s37
	v_add3_u32 v15, v82, v15, s37
	v_add3_u32 v10, v85, v10, s37
	v_and_b32_e32 v11, 0xffff0000, v11
	v_and_b32_e32 v15, 0xffff0000, v15
	v_or_b32_sdwa v11, v11, v10 dst_sel:DWORD dst_unused:UNUSED_PAD src0_sel:DWORD src1_sel:WORD_1
	v_or_b32_sdwa v10, v15, v14 dst_sel:DWORD dst_unused:UNUSED_PAD src0_sel:DWORD src1_sel:WORD_1
	v_ashrrev_i32_e32 v13, 31, v12
	global_store_dwordx2 v[4:5], v[10:11], off offset:96
	v_and_b32_sdwa v11, v80, v183 dst_sel:DWORD dst_unused:UNUSED_PAD src0_sel:WORD_1 src1_sel:DWORD
	v_lshlrev_b64 v[4:5], 11, v[12:13]
	v_add3_u32 v12, v80, v11, s37
	v_and_b32_sdwa v11, v79, v183 dst_sel:DWORD dst_unused:UNUSED_PAD src0_sel:WORD_1 src1_sel:DWORD
	v_and_b32_sdwa v13, v78, v183 dst_sel:DWORD dst_unused:UNUSED_PAD src0_sel:WORD_1 src1_sel:DWORD
	v_and_b32_sdwa v10, v81, v183 dst_sel:DWORD dst_unused:UNUSED_PAD src0_sel:WORD_1 src1_sel:DWORD
	v_add3_u32 v11, v79, v11, s37
	v_add3_u32 v13, v78, v13, s37
	v_lshl_add_u64 v[4:5], s[12:13], 0, v[4:5]
	v_add3_u32 v10, v81, v10, s37
	v_and_b32_e32 v11, 0xffff0000, v11
	v_and_b32_e32 v13, 0xffff0000, v13
	v_lshl_add_u64 v[4:5], v[4:5], 0, v[6:7]
	v_or_b32_sdwa v11, v11, v10 dst_sel:DWORD dst_unused:UNUSED_PAD src0_sel:DWORD src1_sel:WORD_1
	v_or_b32_sdwa v10, v13, v12 dst_sel:DWORD dst_unused:UNUSED_PAD src0_sel:DWORD src1_sel:WORD_1
	global_store_dwordx2 v[4:5], v[10:11], off
	v_and_b32_sdwa v11, v76, v183 dst_sel:DWORD dst_unused:UNUSED_PAD src0_sel:WORD_1 src1_sel:DWORD
	v_add3_u32 v12, v76, v11, s37
	v_and_b32_sdwa v11, v75, v183 dst_sel:DWORD dst_unused:UNUSED_PAD src0_sel:WORD_1 src1_sel:DWORD
	v_and_b32_sdwa v13, v74, v183 dst_sel:DWORD dst_unused:UNUSED_PAD src0_sel:WORD_1 src1_sel:DWORD
	v_and_b32_sdwa v10, v77, v183 dst_sel:DWORD dst_unused:UNUSED_PAD src0_sel:WORD_1 src1_sel:DWORD
; __device__ __forceinline__ unsigned pack2(float a, float b) { return (unsigned)f2bf(a) | ((unsigned)f2bf(b) << 16); }
; __device__ __forceinline__ void phase_gemm_merge(const Params& p, char* smem) {
;     ...
; #pragma unroll
;     for (int i = 0; i < 4; ++i) {
;       const int m = mt * 128 + wm * 64 + i * 16 + (lane & 15);
; #pragma unroll
;       for (int j = 0; j < 4; ++j) {
;         const int n = nt * 128 + wn * 64 + j * 16 + (lane >> 4) * 4;
;         uint2 o;
;         o.x = pack2(outv[i][j][0], outv[i][j][1]);
;         o.y = pack2(outv[i][j][2], outv[i][j][3]);
;         *(uint2*)(MG + (size_t)m * 1024 + n) = o;
;       }
	v_add3_u32 v11, v75, v11, s37
	v_add3_u32 v13, v74, v13, s37
	v_add3_u32 v10, v77, v10, s37
	v_and_b32_e32 v11, 0xffff0000, v11
	v_and_b32_e32 v13, 0xffff0000, v13
	v_or_b32_sdwa v11, v11, v10 dst_sel:DWORD dst_unused:UNUSED_PAD src0_sel:DWORD src1_sel:WORD_1
	v_or_b32_sdwa v10, v13, v12 dst_sel:DWORD dst_unused:UNUSED_PAD src0_sel:DWORD src1_sel:WORD_1
	global_store_dwordx2 v[4:5], v[10:11], off offset:32
	v_and_b32_sdwa v11, v72, v183 dst_sel:DWORD dst_unused:UNUSED_PAD src0_sel:WORD_1 src1_sel:DWORD
	v_add3_u32 v12, v72, v11, s37
	v_and_b32_sdwa v11, v71, v183 dst_sel:DWORD dst_unused:UNUSED_PAD src0_sel:WORD_1 src1_sel:DWORD
	v_and_b32_sdwa v13, v70, v183 dst_sel:DWORD dst_unused:UNUSED_PAD src0_sel:WORD_1 src1_sel:DWORD
	v_and_b32_sdwa v10, v73, v183 dst_sel:DWORD dst_unused:UNUSED_PAD src0_sel:WORD_1 src1_sel:DWORD
	v_add3_u32 v11, v71, v11, s37
	v_add3_u32 v13, v70, v13, s37
	v_add3_u32 v10, v73, v10, s37
	v_and_b32_e32 v11, 0xffff0000, v11
	v_and_b32_e32 v13, 0xffff0000, v13
	v_or_b32_sdwa v11, v11, v10 dst_sel:DWORD dst_unused:UNUSED_PAD src0_sel:DWORD src1_sel:WORD_1
	v_or_b32_sdwa v10, v13, v12 dst_sel:DWORD dst_unused:UNUSED_PAD src0_sel:DWORD src1_sel:WORD_1
	global_store_dwordx2 v[4:5], v[10:11], off offset:64
	v_and_b32_sdwa v11, v68, v183 dst_sel:DWORD dst_unused:UNUSED_PAD src0_sel:WORD_1 src1_sel:DWORD
	v_add3_u32 v12, v68, v11, s37
	v_and_b32_sdwa v11, v67, v183 dst_sel:DWORD dst_unused:UNUSED_PAD src0_sel:WORD_1 src1_sel:DWORD
	v_and_b32_sdwa v13, v66, v183 dst_sel:DWORD dst_unused:UNUSED_PAD src0_sel:WORD_1 src1_sel:DWORD
	v_and_b32_sdwa v10, v69, v183 dst_sel:DWORD dst_unused:UNUSED_PAD src0_sel:WORD_1 src1_sel:DWORD
	v_add3_u32 v11, v67, v11, s37
	v_add3_u32 v13, v66, v13, s37
	v_add3_u32 v10, v69, v10, s37
	v_and_b32_e32 v11, 0xffff0000, v11
	v_and_b32_e32 v13, 0xffff0000, v13
	v_ashrrev_i32_e32 v9, 31, v8
	v_or_b32_sdwa v11, v11, v10 dst_sel:DWORD dst_unused:UNUSED_PAD src0_sel:DWORD src1_sel:WORD_1
	v_or_b32_sdwa v10, v13, v12 dst_sel:DWORD dst_unused:UNUSED_PAD src0_sel:DWORD src1_sel:WORD_1
	global_store_dwordx2 v[4:5], v[10:11], off offset:96
	v_lshlrev_b64 v[4:5], 11, v[8:9]
	v_lshl_add_u64 v[4:5], s[12:13], 0, v[4:5]
	v_lshl_add_u64 v[4:5], v[4:5], 0, v[6:7]
	v_and_b32_sdwa v7, v64, v183 dst_sel:DWORD dst_unused:UNUSED_PAD src0_sel:WORD_1 src1_sel:DWORD
	v_add3_u32 v8, v64, v7, s37
	v_and_b32_sdwa v7, v63, v183 dst_sel:DWORD dst_unused:UNUSED_PAD src0_sel:WORD_1 src1_sel:DWORD
	v_and_b32_sdwa v9, v62, v183 dst_sel:DWORD dst_unused:UNUSED_PAD src0_sel:WORD_1 src1_sel:DWORD
	v_and_b32_sdwa v6, v65, v183 dst_sel:DWORD dst_unused:UNUSED_PAD src0_sel:WORD_1 src1_sel:DWORD
	v_add3_u32 v7, v63, v7, s37
	v_add3_u32 v9, v62, v9, s37
	v_add3_u32 v6, v65, v6, s37
	v_and_b32_e32 v7, 0xffff0000, v7
	v_and_b32_e32 v9, 0xffff0000, v9
	v_or_b32_sdwa v7, v7, v6 dst_sel:DWORD dst_unused:UNUSED_PAD src0_sel:DWORD src1_sel:WORD_1
	v_or_b32_sdwa v6, v9, v8 dst_sel:DWORD dst_unused:UNUSED_PAD src0_sel:DWORD src1_sel:WORD_1
	global_store_dwordx2 v[4:5], v[6:7], off
	v_and_b32_sdwa v7, v60, v183 dst_sel:DWORD dst_unused:UNUSED_PAD src0_sel:WORD_1 src1_sel:DWORD
	v_add3_u32 v8, v60, v7, s37
	v_and_b32_sdwa v7, v59, v183 dst_sel:DWORD dst_unused:UNUSED_PAD src0_sel:WORD_1 src1_sel:DWORD
	v_and_b32_sdwa v9, v58, v183 dst_sel:DWORD dst_unused:UNUSED_PAD src0_sel:WORD_1 src1_sel:DWORD
	v_and_b32_sdwa v6, v61, v183 dst_sel:DWORD dst_unused:UNUSED_PAD src0_sel:WORD_1 src1_sel:DWORD
	v_add3_u32 v7, v59, v7, s37
	v_add3_u32 v9, v58, v9, s37
	v_add3_u32 v6, v61, v6, s37
	v_and_b32_e32 v7, 0xffff0000, v7
	v_and_b32_e32 v9, 0xffff0000, v9
	v_or_b32_sdwa v7, v7, v6 dst_sel:DWORD dst_unused:UNUSED_PAD src0_sel:DWORD src1_sel:WORD_1
	v_or_b32_sdwa v6, v9, v8 dst_sel:DWORD dst_unused:UNUSED_PAD src0_sel:DWORD src1_sel:WORD_1
	global_store_dwordx2 v[4:5], v[6:7], off offset:32
	v_and_b32_sdwa v7, v56, v183 dst_sel:DWORD dst_unused:UNUSED_PAD src0_sel:WORD_1 src1_sel:DWORD
	v_add3_u32 v8, v56, v7, s37
	v_and_b32_sdwa v7, v55, v183 dst_sel:DWORD dst_unused:UNUSED_PAD src0_sel:WORD_1 src1_sel:DWORD
	v_and_b32_sdwa v9, v54, v183 dst_sel:DWORD dst_unused:UNUSED_PAD src0_sel:WORD_1 src1_sel:DWORD
	v_and_b32_sdwa v6, v57, v183 dst_sel:DWORD dst_unused:UNUSED_PAD src0_sel:WORD_1 src1_sel:DWORD
	v_add3_u32 v7, v55, v7, s37
	v_add3_u32 v9, v54, v9, s37
	v_add3_u32 v6, v57, v6, s37
	v_and_b32_e32 v7, 0xffff0000, v7
	v_and_b32_e32 v9, 0xffff0000, v9
	v_or_b32_sdwa v7, v7, v6 dst_sel:DWORD dst_unused:UNUSED_PAD src0_sel:DWORD src1_sel:WORD_1
	v_or_b32_sdwa v6, v9, v8 dst_sel:DWORD dst_unused:UNUSED_PAD src0_sel:DWORD src1_sel:WORD_1
	global_store_dwordx2 v[4:5], v[6:7], off offset:64
	v_and_b32_sdwa v6, v1, v183 dst_sel:DWORD dst_unused:UNUSED_PAD src0_sel:WORD_1 src1_sel:DWORD
	v_and_b32_sdwa v7, v0, v183 dst_sel:DWORD dst_unused:UNUSED_PAD src0_sel:WORD_1 src1_sel:DWORD
	v_add3_u32 v0, v0, v7, s37
	v_add3_u32 v1, v1, v6, s37
	v_and_b32_sdwa v6, v53, v183 dst_sel:DWORD dst_unused:UNUSED_PAD src0_sel:WORD_1 src1_sel:DWORD
	v_and_b32_sdwa v7, v52, v183 dst_sel:DWORD dst_unused:UNUSED_PAD src0_sel:WORD_1 src1_sel:DWORD
	v_add3_u32 v6, v53, v6, s37
	v_add3_u32 v7, v52, v7, s37
	s_add_i32 s24, s24, 1
	v_and_b32_e32 v6, 0xffff0000, v6
	v_and_b32_e32 v7, 0xffff0000, v7
	s_cmp_eq_u32 s24, s22
	v_or_b32_sdwa v1, v6, v1 dst_sel:DWORD dst_unused:UNUSED_PAD src0_sel:DWORD src1_sel:WORD_1
	v_or_b32_sdwa v0, v7, v0 dst_sel:DWORD dst_unused:UNUSED_PAD src0_sel:DWORD src1_sel:WORD_1
	s_cselect_b64 s[12:13], -1, 0
	s_mov_b32 s31, 0x18000
	global_store_dwordx2 v[4:5], v[0:1], off offset:96
	s_branch .LBB0_18
